# P8 prompt unit: softmax probabilities go registers -> LDS A-tile image (ds_write_b64) instead of global scratch + LDS-DMA; A-side stages of the PV GEMM deleted, vmcnt recounted, 24 KB static LDS for o
# speedup vs baseline: 1.0509x; 1.0178x over previous
.LBB0_985:
	s_mov_b32 s99, 0x20400
	v_mov_b32_e32 v14, v136
	s_barrier
	s_ashr_i32 s33, s47, 5
	v_bfe_i32 v2, v14, 27, 1
	v_lshlrev_b32_e32 v1, 4, v14
	v_lshrrev_b32_e32 v2, 22, v2
	v_add_u32_e32 v2, v1, v2
	v_and_b32_e32 v2, 0xfffffc00, v2
	v_sub_u32_e32 v2, v1, v2
	v_lshrrev_b32_e32 v3, 4, v2
	v_ashrrev_i32_e32 v0, 31, v14
	v_bitop3_b32 v2, v3, v2, 32 bitop3:0x6c
	v_lshrrev_b32_e32 v0, 26, v0
	v_ashrrev_i32_e32 v4, 31, v2
	v_add_u32_e32 v0, v14, v0
	v_lshrrev_b32_e32 v4, 26, v4
	v_ashrrev_i32_e32 v0, 6, v0
	v_add_u32_e32 v4, v2, v4
	v_lshlrev_b32_e32 v3, 3, v0
	v_ashrrev_i32_e32 v5, 6, v4
	v_and_b32_e32 v4, 0xc0, v4
	v_and_b32_e32 v3, -16, v3
	v_lshlrev_b32_e32 v0, 5, v0
	v_sub_u32_e32 v2, v2, v4
	v_add_u32_e32 v3, v5, v3
	v_and_b32_e32 v0, 32, v0
	v_ashrrev_i16_sdwa v2, v133, sext(v2) dst_sel:DWORD dst_unused:UNUSED_PAD src0_sel:DWORD src1_sel:BYTE_0
	v_add_u32_sdwa v0, v0, sext(v2) dst_sel:DWORD dst_unused:UNUSED_PAD src0_sel:DWORD src1_sel:WORD_0
	v_lshlrev_b32_e32 v2, 11, v3
	v_lshl_add_u32 v0, v0, 1, v2
	v_mad_u64_u32 v[6:7], s[52:53], v3, s37, v[0:1]
	v_add_u32_e32 v1, 0x2000, v1
	v_ashrrev_i32_e32 v2, 31, v1
	v_lshrrev_b32_e32 v2, 22, v2
	v_add_u32_e32 v2, v1, v2
	v_ashrrev_i32_e32 v2, 10, v2
	s_lshl_b32 s26, s33, 11
	s_and_b32 s27, s3, 0x700
	v_mul_i32_i24_e32 v3, 0x400, v2
	s_or_b32 s26, s26, s27
	v_sub_u32_e32 v1, v1, v3
	s_ashr_i32 s27, s26, 31
	v_lshrrev_b32_e32 v3, 4, v1
	s_bfe_u32 s50, s47, 0x20003
	s_lshl_b64 s[28:29], s[26:27], 11
	v_bitop3_b32 v1, v3, v1, 32 bitop3:0x6c
	s_add_u32 s27, s62, s28
	v_ashrrev_i32_e32 v4, 31, v1
	s_addc_u32 s28, s63, s29
	s_lshl_b32 s29, s50, 9
	v_lshrrev_b32_e32 v4, 26, v4
	s_add_u32 s30, s27, s29
	v_add_u32_e32 v4, v1, v4
	s_addc_u32 s31, s28, 0
	s_lshl_b32 s27, s33, 2
	v_lshlrev_b32_e32 v3, 3, v2
	v_ashrrev_i32_e32 v5, 6, v4
	v_and_b32_e32 v4, 0xc0, v4
	s_or_b32 s28, s27, s50
	v_and_b32_e32 v3, -16, v3
	v_lshlrev_b32_e32 v2, 5, v2
	v_sub_u32_e32 v1, v1, v4
	s_ashr_i32 s29, s28, 31
	v_add_u32_e32 v3, v5, v3
	v_and_b32_e32 v2, 32, v2
	v_ashrrev_i16_sdwa v1, v133, sext(v1) dst_sel:DWORD dst_unused:UNUSED_PAD src0_sel:DWORD src1_sel:BYTE_0
	s_lshl_b64 s[34:35], s[28:29], 17
	v_add_u32_sdwa v1, v2, sext(v1) dst_sel:DWORD dst_unused:UNUSED_PAD src0_sel:DWORD src1_sel:WORD_0
	v_lshlrev_b32_e32 v2, 11, v3
	s_add_u32 s34, s64, s34
	v_readfirstlane_b32 s27, v14
	v_lshl_add_u32 v2, v1, 1, v2
	s_addc_u32 s35, s65, s35
	v_mad_u64_u32 v[4:5], s[52:53], v3, s37, v[2:3]
	s_ashr_i32 s51, s27, 6
	s_lshl_b32 s53, s51, 10
	s_add_i32 s76, s53, 0
	s_add_i32 m0, s76, 0x10000
	s_ashr_i32 s33, s27, 8
	global_load_lds_dwordx4 v6, s[34:35]
	s_add_i32 m0, s76, 0x12000
	s_add_i32 s77, s76, 0x2000
	global_load_lds_dwordx4 v4, s[34:35]
	s_mov_b32 m0, s76
	s_add_u32 s56, s34, 0x10000
	global_load_lds_dwordx4 v0, s[30:31]
	s_mov_b32 m0, s77
	s_addc_u32 s57, s35, 0
	global_load_lds_dwordx4 v2, s[30:31]
	s_add_i32 m0, s76, 0x14000
	v_mov_b32_e32 v128, v6
	global_load_lds_dwordx4 v6, s[56:57]
	s_add_i32 m0, s76, 0x16000
	s_add_u32 s72, s30, 0x40000
	global_load_lds_dwordx4 v4, s[56:57]
	s_addc_u32 s73, s31, 0
	s_add_i32 s57, s76, 0x4000
	s_mov_b32 m0, s57
	s_add_i32 s52, s76, 0x6000
	global_load_lds_dwordx4 v0, s[72:73]
	s_mov_b32 m0, s52
	v_mov_b32_e32 v5, v129
	global_load_lds_dwordx4 v2, s[72:73]
	v_mov_b32_e32 v1, v129
	v_mov_b32_e32 v3, v129
	v_lshl_add_u64 v[12:13], s[34:35], 0, v[128:129]
	v_lshl_add_u64 v[10:11], s[34:35], 0, v[4:5]
	v_lshl_add_u64 v[6:7], s[30:31], 0, v[0:1]
	s_cmp_lg_u32 s33, 1
	v_lshl_add_u64 v[8:9], s[30:31], 0, v[2:3]
	s_cbranch_scc1 .LBB0_987
	s_barrier

.LBB0_989:
	v_max3_f32 v134, v124, s46, v125
	v_max3_f32 v134, v134, v126, v127
	v_max3_f32 v134, v134, v116, v117
	v_and_b32_e32 v131, 64, v137
	v_max3_f32 v134, v134, v118, v119
	v_xor_b32_e32 v130, 16, v137
	v_add_u32_e32 v131, 64, v131
	v_max3_f32 v134, v134, v120, v121
	v_cmp_lt_i32_e32 vcc, v130, v131
	v_max3_f32 v134, v134, v122, v123
	v_max3_f32 v134, v134, v112, v113
	v_cndmask_b32_e32 v130, v137, v130, vcc
	v_lshlrev_b32_e32 v171, 2, v130
	v_max3_f32 v134, v134, v114, v115
	ds_bpermute_b32 v135, v171, v134
	v_xor_b32_e32 v130, 32, v137
	v_cmp_lt_i32_e32 vcc, v130, v131
	v_mov_b32_e32 v169, v136
	s_nop 0
	v_cndmask_b32_e32 v130, v137, v130, vcc
	v_lshlrev_b32_e32 v172, 2, v130
	s_waitcnt lgkmcnt(0)
	v_max_f32_e32 v130, v135, v135
	v_max_f32_e32 v134, v134, v130
	ds_bpermute_b32 v135, v172, v134
	v_bfe_u32 v128, v169, 6, 2
	v_and_b32_e32 v170, 15, v169
	v_bfe_u32 v168, v169, 4, 2
	v_lshl_add_u32 v138, v128, 10, s99
	v_and_b32_e32 v130, 0xffffff00, v169
	v_lshlrev_b32_e32 v131, 2, v170
	v_cmp_eq_u32_e32 vcc, 0, v168
	v_add3_u32 v173, v138, v130, v131
	s_and_saveexec_b64 s[30:31], vcc
	s_cbranch_execz .LBB0_991
	s_waitcnt lgkmcnt(0)
	v_max_f32_e32 v135, v135, v135
	v_max_f32_e32 v134, v134, v134
	v_max_f32_e32 v134, v134, v135
	ds_write_b32 v173, v134

.LBB0_1005:
	s_or_b64 exec, exec, s[30:31]
	v_add3_u32 v134, s99, v130, v131
	v_add_u32_e32 v142, 0xc00, v134
	s_waitcnt vmcnt(0) lgkmcnt(0)
	s_barrier
	ds_read2_b32 v[160:161], v134 offset1:16
	v_add_u32_e32 v140, 0x800, v134
	ds_read2_b32 v[166:167], v142 offset1:16
	ds_read2_b32 v[164:165], v140 offset1:16
	v_add_u32_e32 v138, 0x400, v134
	ds_read2_b32 v[162:163], v138 offset1:16
	ds_read2_b32 v[152:153], v134 offset0:32 offset1:48
	ds_read2_b32 v[154:155], v138 offset0:32 offset1:48
	ds_read2_b32 v[156:157], v140 offset0:32 offset1:48
	ds_read2_b32 v[158:159], v142 offset0:32 offset1:48
	ds_read2_b32 v[144:145], v134 offset0:128 offset1:144
	ds_read2_b32 v[146:147], v138 offset0:128 offset1:144
	ds_read2_b32 v[148:149], v140 offset0:128 offset1:144
	ds_read2_b32 v[150:151], v142 offset0:128 offset1:144
	s_waitcnt lgkmcnt(10)
	v_max_f32_e32 v130, v166, v166
	s_waitcnt lgkmcnt(9)
	v_max_f32_e32 v131, v164, v164
	v_max_f32_e32 v130, v131, v130
	s_waitcnt lgkmcnt(8)
	v_max3_f32 v135, v160, v162, v130
	v_sub_f32_e32 v124, v124, v135
	v_mul_f32_e32 v124, 0x3d800000, v124
	v_sub_f32_e32 v125, v125, v135
	v_mul_f32_e32 v124, 0x3fb8aa3b, v124
	v_mul_f32_e32 v125, 0x3d800000, v125
	v_sub_f32_e32 v126, v126, v135
	v_exp_f32_e32 v124, v124
	v_mul_f32_e32 v125, 0x3fb8aa3b, v125
	v_mul_f32_e32 v126, 0x3d800000, v126
	v_sub_f32_e32 v127, v127, v135
	v_exp_f32_e32 v125, v125
	v_mul_f32_e32 v126, 0x3fb8aa3b, v126
	v_mul_f32_e32 v127, 0x3d800000, v127
	v_exp_f32_e32 v126, v126
	v_mul_f32_e32 v127, 0x3fb8aa3b, v127
	v_exp_f32_e32 v127, v127
	v_add_f32_e32 v130, 0, v124
	v_sub_f32_e32 v116, v116, v135
	v_sub_f32_e32 v118, v118, v135
	v_add_f32_e32 v130, v125, v130
	v_mul_f32_e32 v116, 0x3d800000, v116
	v_sub_f32_e32 v117, v117, v135
	v_mul_f32_e32 v118, 0x3d800000, v118
	v_add_f32_e32 v130, v126, v130
	v_mul_f32_e32 v116, 0x3fb8aa3b, v116
	v_mul_f32_e32 v117, 0x3d800000, v117
	v_mul_f32_e32 v118, 0x3fb8aa3b, v118
	v_add_f32_e32 v139, v127, v130
	v_exp_f32_e32 v116, v116
	v_mul_f32_e32 v117, 0x3fb8aa3b, v117
	v_exp_f32_e32 v130, v118
	v_sub_f32_e32 v118, v119, v135
	v_exp_f32_e32 v117, v117
	v_mul_f32_e32 v118, 0x3d800000, v118
	v_mul_f32_e32 v118, 0x3fb8aa3b, v118
	v_exp_f32_e32 v131, v118
	v_add_f32_e32 v118, v116, v139
	v_add_f32_e32 v118, v117, v118
	v_add_f32_e32 v118, v130, v118
	v_add_f32_e32 v139, v131, v118
	v_sub_f32_e32 v118, v120, v135
	v_mul_f32_e32 v118, 0x3d800000, v118
	v_sub_f32_e32 v119, v121, v135
	v_mul_f32_e32 v118, 0x3fb8aa3b, v118
	v_mul_f32_e32 v119, 0x3d800000, v119
	v_sub_f32_e32 v120, v122, v135
	v_exp_f32_e32 v118, v118
	v_mul_f32_e32 v119, 0x3fb8aa3b, v119
	v_mul_f32_e32 v120, 0x3d800000, v120
	v_sub_f32_e32 v121, v123, v135
	v_exp_f32_e32 v119, v119
	v_mul_f32_e32 v120, 0x3fb8aa3b, v120
	v_mul_f32_e32 v121, 0x3d800000, v121
	v_sub_f32_e32 v112, v112, v135
	v_exp_f32_e32 v120, v120
	v_mul_f32_e32 v121, 0x3fb8aa3b, v121
	v_mul_f32_e32 v112, 0x3d800000, v112
	v_sub_f32_e32 v113, v113, v135
	v_exp_f32_e32 v121, v121
	v_mul_f32_e32 v112, 0x3fb8aa3b, v112
	v_mul_f32_e32 v113, 0x3d800000, v113
	v_sub_f32_e32 v114, v114, v135
	v_add_f32_e32 v122, v118, v139
	v_exp_f32_e32 v112, v112
	v_mul_f32_e32 v113, 0x3fb8aa3b, v113
	v_mul_f32_e32 v114, 0x3d800000, v114
	v_sub_f32_e32 v115, v115, v135
	v_add_f32_e32 v122, v119, v122
	v_exp_f32_e32 v113, v113
	v_mul_f32_e32 v114, 0x3fb8aa3b, v114
	v_mul_f32_e32 v115, 0x3d800000, v115
	v_add_f32_e32 v122, v120, v122
	v_exp_f32_e32 v114, v114
	v_mul_f32_e32 v115, 0x3fb8aa3b, v115
	v_add_f32_e32 v122, v121, v122
	v_exp_f32_e32 v115, v115
	v_add_f32_e32 v122, v112, v122
	v_add_f32_e32 v122, v113, v122
	v_add_f32_e32 v122, v114, v122
	v_add_f32_e32 v122, v115, v122
	ds_bpermute_b32 v123, v171, v122
	ds_read2_b32 v[134:135], v134 offset0:160 offset1:176
	ds_read2_b32 v[138:139], v138 offset0:160 offset1:176
	ds_read2_b32 v[140:141], v140 offset0:160 offset1:176
	ds_read2_b32 v[142:143], v142 offset0:160 offset1:176
	s_waitcnt lgkmcnt(0)
	s_barrier
	v_add_f32_e32 v122, v122, v123
	ds_bpermute_b32 v123, v172, v122
	s_and_saveexec_b64 s[30:31], vcc
	s_cbranch_execz .LBB0_1007
	s_waitcnt lgkmcnt(0)
	v_add_f32_e32 v122, v122, v123
	ds_write_b32 v173, v122

.LBB0_1021:
	s_or_b64 exec, exec, s[30:31]
	v_ashrrev_i32_e32 v34, 2, v169
	s_movk_i32 s27, 0xffc0
	v_and_or_b32 v134, v34, s27, v170
	v_lshl_add_u32 v142, v134, 2, s99
	s_waitcnt lgkmcnt(0)
	s_barrier
	v_bfe_u32 v185, v136, 7, 1
	v_lshlrev_b32_e32 v248, 15, v185
	v_lshrrev_b32_e32 v185, 8, v136
	v_lshl_or_b32 v248, v185, 13, v248
	v_bfe_u32 v185, v136, 6, 1
	v_lshl_or_b32 v248, v185, 10, v248
	v_and_b32_e32 v185, 15, v136
	v_lshl_or_b32 v248, v185, 6, v248
	v_bfe_u32 v185, v136, 4, 2
	v_lshl_or_b32 v248, v185, 3, v248
	v_bfe_u32 v185, v136, 3, 1
	v_lshl_or_b32 v248, v185, 5, v248
	v_xor_b32_e32 v249, 32, v248
	v_add_u32_e32 v250, 0x1a000, v248
	v_xor_b32_e32 v251, 32, v250
	v_readfirstlane_b32 s100, v136
	s_lshr_b32 s100, s100, 6
	ds_read2st64_b32 v[34:35], v142 offset1:4
	ds_read2st64_b32 v[138:139], v142 offset0:8 offset1:12
	v_lshlrev_b32_e32 v128, 6, v128
	v_lshl_add_u64 v[140:141], s[0:1], 0, v[128:129]
	v_lshlrev_b32_e32 v128, 3, v168
	s_waitcnt lgkmcnt(1)
	v_add_f32_e32 v34, v34, v35
	s_waitcnt lgkmcnt(0)
	v_add_f32_e32 v34, v34, v138
	v_add_f32_e32 v34, v34, v139
	v_div_scale_f32 v35, s[30:31], v34, v34, 1.0
	v_rcp_f32_e32 v143, v35
	v_lshl_add_u64 v[138:139], v[140:141], 0, v[128:129]
	v_ashrrev_i32_e32 v135, 31, v134
	v_fma_f32 v128, -v35, v143, 1.0
	v_fmac_f32_e32 v143, v128, v143
	v_div_scale_f32 v128, vcc, 1.0, v34, 1.0
	v_mul_f32_e32 v140, v128, v143
	v_fma_f32 v141, -v35, v140, v128
	v_fmac_f32_e32 v140, v141, v143
	v_fma_f32 v35, -v35, v140, v128
	v_div_fmas_f32 v35, v35, v143, v140
	v_div_fixup_f32 v128, v35, v34, 1.0
	v_lshlrev_b64 v[34:35], 9, v[134:135]
	v_pk_mul_f32 v[124:125], v[124:125], v[128:129] op_sel_hi:[1,0]
	v_lshl_add_u64 v[34:35], v[138:139], 0, v[34:35]
	v_pk_mul_f32 v[126:127], v[126:127], v[128:129] op_sel_hi:[1,0]
	v_cvt_pk_bf16_f32 v124, v124, v125
	v_pk_mul_f32 v[116:117], v[116:117], v[128:129] op_sel_hi:[1,0]
	v_cvt_pk_bf16_f32 v125, v126, v127
	ds_write_b64 v248, v[124:125]
	v_pk_mul_f32 v[124:125], v[130:131], v[128:129] op_sel_hi:[1,0]
	v_cvt_pk_bf16_f32 v116, v116, v117
	v_pk_mul_f32 v[118:119], v[118:119], v[128:129] op_sel_hi:[1,0]
	v_cvt_pk_bf16_f32 v117, v124, v125
	v_pk_mul_f32 v[112:113], v[112:113], v[128:129] op_sel_hi:[1,0]
	ds_write_b64 v249, v[116:117]
	v_pk_mul_f32 v[116:117], v[120:121], v[128:129] op_sel_hi:[1,0]
	v_cvt_pk_bf16_f32 v224, v118, v119
	v_pk_mul_f32 v[114:115], v[114:115], v[128:129] op_sel_hi:[1,0]
	v_cvt_pk_bf16_f32 v225, v116, v117
	v_cvt_pk_bf16_f32 v226, v112, v113
	v_cvt_pk_bf16_f32 v227, v114, v115
	v_add_u32_e32 v118, 64, v142
	ds_read2st64_b32 v[112:113], v118 offset1:4
	ds_read2st64_b32 v[114:115], v118 offset0:8 offset1:12
	v_or_b32_e32 v116, 16, v134
	v_ashrrev_i32_e32 v117, 31, v116
	s_waitcnt lgkmcnt(1)
	v_add_f32_e32 v112, v112, v113
	s_waitcnt lgkmcnt(0)
	v_add_f32_e32 v112, v112, v114
	v_add_f32_e32 v112, v112, v115
	v_div_scale_f32 v113, s[30:31], v112, v112, 1.0
	v_rcp_f32_e32 v114, v113
	v_div_scale_f32 v115, vcc, 1.0, v112, 1.0
	v_fma_f32 v119, -v113, v114, 1.0
	v_fmac_f32_e32 v114, v119, v114
	v_mul_f32_e32 v119, v115, v114
	v_fma_f32 v120, -v113, v119, v115
	v_fmac_f32_e32 v119, v120, v114
	v_fma_f32 v113, -v113, v119, v115
	v_div_fmas_f32 v113, v113, v114, v119
	v_div_fixup_f32 v112, v113, v112, 1.0
	v_lshlrev_b64 v[114:115], 9, v[116:117]
	v_pk_mul_f32 v[108:109], v[108:109], v[112:113] op_sel_hi:[1,0]
	v_lshl_add_u64 v[114:115], v[138:139], 0, v[114:115]
	v_pk_mul_f32 v[110:111], v[110:111], v[112:113] op_sel_hi:[1,0]
	v_cvt_pk_bf16_f32 v108, v108, v109
	v_pk_mul_f32 v[100:101], v[100:101], v[112:113] op_sel_hi:[1,0]
	v_cvt_pk_bf16_f32 v109, v110, v111
	ds_write_b64 v248, v[108:109] offset:2048
	v_pk_mul_f32 v[108:109], v[122:123], v[112:113] op_sel_hi:[1,0]
	v_cvt_pk_bf16_f32 v100, v100, v101
	v_pk_mul_f32 v[102:103], v[102:103], v[112:113] op_sel_hi:[1,0]
	v_cvt_pk_bf16_f32 v101, v108, v109
	v_pk_mul_f32 v[96:97], v[96:97], v[112:113] op_sel_hi:[1,0]
	ds_write_b64 v249, v[100:101] offset:2048
	v_pk_mul_f32 v[100:101], v[104:105], v[112:113] op_sel_hi:[1,0]
	v_cvt_pk_bf16_f32 v228, v102, v103
	v_pk_mul_f32 v[98:99], v[98:99], v[112:113] op_sel_hi:[1,0]
	v_cvt_pk_bf16_f32 v229, v100, v101
	v_cvt_pk_bf16_f32 v230, v96, v97
	v_cvt_pk_bf16_f32 v231, v98, v99
	v_add_u32_e32 v96, 0x80, v142
	ds_read2st64_b32 v[98:99], v96 offset1:4
	ds_read2st64_b32 v[100:101], v96 offset0:8 offset1:12
	v_or_b32_e32 v102, 32, v134
	v_ashrrev_i32_e32 v103, 31, v102
	s_waitcnt lgkmcnt(1)
	v_add_f32_e32 v97, v98, v99
	s_waitcnt lgkmcnt(0)
	v_add_f32_e32 v97, v97, v100
	v_add_f32_e32 v97, v97, v101
	v_div_scale_f32 v98, s[30:31], v97, v97, 1.0
	v_rcp_f32_e32 v99, v98
	v_div_scale_f32 v100, vcc, 1.0, v97, 1.0
	v_fma_f32 v101, -v98, v99, 1.0
	v_fmac_f32_e32 v99, v101, v99
	v_mul_f32_e32 v101, v100, v99
	v_fma_f32 v104, -v98, v101, v100
	v_fmac_f32_e32 v101, v104, v99
	v_fma_f32 v98, -v98, v101, v100
	v_div_fmas_f32 v98, v98, v99, v101
	v_div_fixup_f32 v98, v98, v97, 1.0
	v_lshlrev_b64 v[100:101], 9, v[102:103]
	v_pk_mul_f32 v[92:93], v[92:93], v[98:99] op_sel_hi:[1,0]
	v_lshl_add_u64 v[100:101], v[138:139], 0, v[100:101]
	v_pk_mul_f32 v[94:95], v[94:95], v[98:99] op_sel_hi:[1,0]
	v_cvt_pk_bf16_f32 v92, v92, v93
	v_pk_mul_f32 v[84:85], v[84:85], v[98:99] op_sel_hi:[1,0]
	v_cvt_pk_bf16_f32 v93, v94, v95
	ds_write_b64 v248, v[92:93] offset:4096
	v_pk_mul_f32 v[92:93], v[106:107], v[98:99] op_sel_hi:[1,0]
	v_cvt_pk_bf16_f32 v84, v84, v85
	v_pk_mul_f32 v[86:87], v[86:87], v[98:99] op_sel_hi:[1,0]
	v_cvt_pk_bf16_f32 v85, v92, v93
	v_pk_mul_f32 v[80:81], v[80:81], v[98:99] op_sel_hi:[1,0]
	ds_write_b64 v249, v[84:85] offset:4096
	v_pk_mul_f32 v[84:85], v[88:89], v[98:99] op_sel_hi:[1,0]
	v_cvt_pk_bf16_f32 v232, v86, v87
	v_pk_mul_f32 v[82:83], v[82:83], v[98:99] op_sel_hi:[1,0]
	v_cvt_pk_bf16_f32 v233, v84, v85
	v_cvt_pk_bf16_f32 v234, v80, v81
	v_cvt_pk_bf16_f32 v235, v82, v83
	v_add_u32_e32 v80, 0xc0, v142
	ds_read2st64_b32 v[82:83], v80 offset1:4
	ds_read2st64_b32 v[84:85], v80 offset0:8 offset1:12
	v_or_b32_e32 v86, 48, v134
	v_ashrrev_i32_e32 v87, 31, v86
	s_waitcnt lgkmcnt(1)
	v_add_f32_e32 v81, v82, v83
	s_waitcnt lgkmcnt(0)
	v_add_f32_e32 v81, v81, v84
	v_add_f32_e32 v81, v81, v85
	v_div_scale_f32 v82, s[30:31], v81, v81, 1.0
	v_rcp_f32_e32 v83, v82
	v_div_scale_f32 v84, vcc, 1.0, v81, 1.0
	v_fma_f32 v85, -v82, v83, 1.0
	v_fmac_f32_e32 v83, v85, v83
	v_mul_f32_e32 v85, v84, v83
	v_fma_f32 v88, -v82, v85, v84
	v_fmac_f32_e32 v85, v88, v83
	v_fma_f32 v82, -v82, v85, v84
	v_div_fmas_f32 v82, v82, v83, v85
	v_div_fixup_f32 v82, v82, v81, 1.0
	v_lshlrev_b64 v[84:85], 9, v[86:87]
	v_pk_mul_f32 v[76:77], v[76:77], v[82:83] op_sel_hi:[1,0]
	v_lshl_add_u64 v[84:85], v[138:139], 0, v[84:85]
	v_pk_mul_f32 v[78:79], v[78:79], v[82:83] op_sel_hi:[1,0]
	v_cvt_pk_bf16_f32 v76, v76, v77
	v_pk_mul_f32 v[68:69], v[68:69], v[82:83] op_sel_hi:[1,0]
	v_cvt_pk_bf16_f32 v77, v78, v79
	ds_write_b64 v248, v[76:77] offset:6144
	v_pk_mul_f32 v[76:77], v[90:91], v[82:83] op_sel_hi:[1,0]
	v_cvt_pk_bf16_f32 v68, v68, v69
	v_pk_mul_f32 v[70:71], v[70:71], v[82:83] op_sel_hi:[1,0]
	v_cvt_pk_bf16_f32 v69, v76, v77
	ds_write_b64 v249, v[68:69] offset:6144
	v_pk_mul_f32 v[68:69], v[74:75], v[82:83] op_sel_hi:[1,0]
	v_cvt_pk_bf16_f32 v236, v70, v71
	v_pk_mul_f32 v[66:67], v[66:67], v[82:83] op_sel_hi:[1,0]
	v_cvt_pk_bf16_f32 v237, v68, v69
	v_pk_mul_f32 v[68:69], v[72:73], v[82:83] op_sel_hi:[1,0]
	v_cvt_pk_bf16_f32 v238, v68, v69
	v_cvt_pk_bf16_f32 v239, v66, v67
	ds_read2st64_b32 v[66:67], v142 offset0:2 offset1:6
	ds_read2st64_b32 v[68:69], v142 offset0:10 offset1:14
	s_mov_b32 s27, 0x10000
	s_waitcnt lgkmcnt(1)
	v_add_f32_e32 v66, v66, v67
	s_waitcnt lgkmcnt(0)
	v_add_f32_e32 v66, v66, v68
	v_add_f32_e32 v66, v66, v69
	v_div_scale_f32 v67, s[30:31], v66, v66, 1.0
	v_rcp_f32_e32 v68, v67
	v_div_scale_f32 v69, vcc, 1.0, v66, 1.0
	s_mov_b64 s[30:31], 0x10000
	v_fma_f32 v70, -v67, v68, 1.0
	v_fmac_f32_e32 v68, v70, v68
	v_mul_f32_e32 v70, v69, v68
	v_fma_f32 v71, -v67, v70, v69
	v_fmac_f32_e32 v70, v71, v68
	v_fma_f32 v67, -v67, v70, v69
	v_div_fmas_f32 v67, v67, v68, v70
	v_div_fixup_f32 v66, v67, v66, 1.0
	v_pk_mul_f32 v[56:57], v[56:57], v[66:67] op_sel_hi:[1,0]
	v_lshl_add_u64 v[68:69], v[34:35], 0, s[30:31]
	v_pk_mul_f32 v[62:63], v[62:63], v[66:67] op_sel_hi:[1,0]
	v_pk_mul_f32 v[60:61], v[60:61], v[66:67] op_sel_hi:[1,0]
	v_pk_mul_f32 v[58:59], v[58:59], v[66:67] op_sel_hi:[1,0]
	v_cvt_pk_bf16_f32 v56, v56, v57
	v_pk_mul_f32 v[52:53], v[52:53], v[66:67] op_sel_hi:[1,0]
	v_cvt_pk_bf16_f32 v57, v58, v59
	v_cvt_pk_bf16_f32 v60, v60, v61
	v_cvt_pk_bf16_f32 v61, v62, v63
	v_add_co_u32_e32 v62, vcc, s27, v34
	ds_write_b64 v249, v[56:57] offset:16384
	v_pk_mul_f32 v[56:57], v[64:65], v[66:67] op_sel_hi:[1,0]
	v_cvt_pk_bf16_f32 v208, v52, v53
	v_addc_co_u32_e32 v63, vcc, 0, v35, vcc
	v_cvt_pk_bf16_f32 v209, v56, v57
	v_pk_mul_f32 v[52:53], v[54:55], v[66:67] op_sel_hi:[1,0]
	ds_write_b64 v248, v[60:61] offset:16384
	v_pk_mul_f32 v[50:51], v[50:51], v[66:67] op_sel_hi:[1,0]
	v_cvt_pk_bf16_f32 v210, v52, v53
	s_nop 0
	v_cvt_pk_bf16_f32 v211, v50, v51
	ds_read2st64_b32 v[50:51], v118 offset0:2 offset1:6
	ds_read2st64_b32 v[52:53], v118 offset0:10 offset1:14
	s_mov_b32 s27, 0x12000
	s_waitcnt lgkmcnt(1)
	v_add_f32_e32 v50, v50, v51
	s_waitcnt lgkmcnt(0)
	v_add_f32_e32 v50, v50, v52
	v_add_f32_e32 v50, v50, v53
	v_div_scale_f32 v51, s[30:31], v50, v50, 1.0
	v_rcp_f32_e32 v52, v51
	v_div_scale_f32 v53, vcc, 1.0, v50, 1.0
	s_mov_b64 s[30:31], 0x12000
	v_fma_f32 v54, -v51, v52, 1.0
	v_fmac_f32_e32 v52, v54, v52
	v_mul_f32_e32 v54, v53, v52
	v_fma_f32 v55, -v51, v54, v53
	v_fmac_f32_e32 v54, v55, v52
	v_fma_f32 v51, -v51, v54, v53
	v_div_fmas_f32 v51, v51, v52, v54
	v_div_fixup_f32 v50, v51, v50, 1.0
	v_pk_mul_f32 v[46:47], v[46:47], v[50:51] op_sel_hi:[1,0]
	v_pk_mul_f32 v[44:45], v[44:45], v[50:51] op_sel_hi:[1,0]
	v_pk_mul_f32 v[36:37], v[36:37], v[50:51] op_sel_hi:[1,0]
	v_cvt_pk_bf16_f32 v44, v44, v45
	v_cvt_pk_bf16_f32 v45, v46, v47
	v_add_co_u32_e32 v46, vcc, s27, v34
	v_lshl_add_u64 v[52:53], v[34:35], 0, s[30:31]
	s_nop 0
	v_addc_co_u32_e32 v47, vcc, 0, v35, vcc
	v_pk_mul_f32 v[40:41], v[40:41], v[50:51] op_sel_hi:[1,0]
	v_pk_mul_f32 v[38:39], v[38:39], v[50:51] op_sel_hi:[1,0]
	v_cvt_pk_bf16_f32 v212, v36, v37
	v_pk_mul_f32 v[32:33], v[32:33], v[50:51] op_sel_hi:[1,0]
	v_cvt_pk_bf16_f32 v213, v38, v39
	ds_write_b64 v248, v[44:45] offset:18432
	v_pk_mul_f32 v[42:43], v[42:43], v[50:51] op_sel_hi:[1,0]
	v_cvt_pk_bf16_f32 v40, v40, v41
	v_cvt_pk_bf16_f32 v41, v42, v43
	ds_write_b64 v249, v[40:41] offset:18432
	v_pk_mul_f32 v[36:37], v[48:49], v[50:51] op_sel_hi:[1,0]
	v_cvt_pk_bf16_f32 v214, v32, v33
	s_nop 0
	v_cvt_pk_bf16_f32 v215, v36, v37
	ds_read2st64_b32 v[32:33], v96 offset0:2 offset1:6
	ds_read2st64_b32 v[36:37], v96 offset0:10 offset1:14
	s_mov_b32 s27, 0x14000
	s_waitcnt lgkmcnt(1)
	v_add_f32_e32 v32, v32, v33
	s_waitcnt lgkmcnt(0)
	v_add_f32_e32 v32, v32, v36
	v_add_f32_e32 v32, v32, v37
	v_div_scale_f32 v33, s[30:31], v32, v32, 1.0
	v_rcp_f32_e32 v36, v33
	v_div_scale_f32 v37, vcc, 1.0, v32, 1.0
	s_mov_b64 s[30:31], 0x14000
	v_fma_f32 v38, -v33, v36, 1.0
	v_fmac_f32_e32 v36, v38, v36
	v_mul_f32_e32 v38, v37, v36
	v_fma_f32 v39, -v33, v38, v37
	v_fmac_f32_e32 v38, v39, v36
	v_fma_f32 v33, -v33, v38, v37
	v_div_fmas_f32 v33, v33, v36, v38
	v_div_fixup_f32 v32, v33, v32, 1.0
	v_pk_mul_f32 v[30:31], v[30:31], v[32:33] op_sel_hi:[1,0]
	v_pk_mul_f32 v[28:29], v[28:29], v[32:33] op_sel_hi:[1,0]
	v_lshl_add_u64 v[36:37], v[34:35], 0, s[30:31]
	v_cvt_pk_bf16_f32 v28, v28, v29
	v_cvt_pk_bf16_f32 v29, v30, v31
	v_add_co_u32_e32 v30, vcc, s27, v34
	v_pk_mul_f32 v[24:25], v[24:25], v[32:33] op_sel_hi:[1,0]
	s_nop 0
	v_addc_co_u32_e32 v31, vcc, 0, v35, vcc
	v_pk_mul_f32 v[20:21], v[20:21], v[32:33] op_sel_hi:[1,0]
	v_pk_mul_f32 v[16:17], v[16:17], v[32:33] op_sel_hi:[1,0]
	ds_write_b64 v248, v[28:29] offset:20480
	v_pk_mul_f32 v[26:27], v[26:27], v[32:33] op_sel_hi:[1,0]
	v_cvt_pk_bf16_f32 v24, v24, v25
	v_pk_mul_f32 v[22:23], v[22:23], v[32:33] op_sel_hi:[1,0]
	v_cvt_pk_bf16_f32 v25, v26, v27
	ds_write_b64 v249, v[24:25] offset:20480
	v_cvt_pk_bf16_f32 v216, v20, v21
	v_cvt_pk_bf16_f32 v217, v22, v23
	v_pk_mul_f32 v[18:19], v[18:19], v[32:33] op_sel_hi:[1,0]
	v_cvt_pk_bf16_f32 v218, v16, v17
	s_nop 0
	v_cvt_pk_bf16_f32 v219, v18, v19
	ds_read2st64_b32 v[16:17], v80 offset0:2 offset1:6
	ds_read2st64_b32 v[18:19], v80 offset0:10 offset1:14
	s_mov_b32 s27, 0x16000
	s_waitcnt lgkmcnt(1)
	v_add_f32_e32 v16, v16, v17
	s_waitcnt lgkmcnt(0)
	v_add_f32_e32 v16, v16, v18
	v_add_f32_e32 v16, v16, v19
	v_div_scale_f32 v17, s[30:31], v16, v16, 1.0
	v_rcp_f32_e32 v18, v17
	v_div_scale_f32 v19, vcc, 1.0, v16, 1.0
	s_mov_b64 s[30:31], 0x16000
	v_fma_f32 v20, -v17, v18, 1.0
	v_fmac_f32_e32 v18, v20, v18
	v_mul_f32_e32 v20, v19, v18
	v_fma_f32 v21, -v17, v20, v19
	v_fmac_f32_e32 v20, v21, v18
	v_fma_f32 v17, -v17, v20, v19
	v_div_fmas_f32 v17, v17, v18, v20
	v_div_fixup_f32 v16, v17, v16, 1.0
	v_pk_mul_f32 v[14:15], v[14:15], v[16:17] op_sel_hi:[1,0]
	v_pk_mul_f32 v[12:13], v[12:13], v[16:17] op_sel_hi:[1,0]
	v_lshl_add_u64 v[18:19], v[34:35], 0, s[30:31]
	v_cvt_pk_bf16_f32 v12, v12, v13
	v_cvt_pk_bf16_f32 v13, v14, v15
	v_add_co_u32_e32 v14, vcc, s27, v34
	v_pk_mul_f32 v[10:11], v[10:11], v[16:17] op_sel_hi:[1,0]
	s_nop 0
	v_addc_co_u32_e32 v15, vcc, 0, v35, vcc
	v_pk_mul_f32 v[8:9], v[8:9], v[16:17] op_sel_hi:[1,0]
	v_pk_mul_f32 v[6:7], v[6:7], v[16:17] op_sel_hi:[1,0]
	v_pk_mul_f32 v[4:5], v[4:5], v[16:17] op_sel_hi:[1,0]
	v_pk_mul_f32 v[0:1], v[0:1], v[16:17] op_sel_hi:[1,0]
	ds_write_b64 v248, v[12:13] offset:22528
	v_cvt_pk_bf16_f32 v8, v8, v9
	v_cvt_pk_bf16_f32 v9, v10, v11
	ds_write_b64 v249, v[8:9] offset:22528
	v_cvt_pk_bf16_f32 v220, v4, v5
	v_cvt_pk_bf16_f32 v221, v6, v7
	v_pk_mul_f32 v[2:3], v[2:3], v[16:17] op_sel_hi:[1,0]
	v_cvt_pk_bf16_f32 v222, v0, v1
	s_nop 0
	v_cvt_pk_bf16_f32 v223, v2, v3
	v_mov_b32_e32 v10, v136
	s_waitcnt vmcnt(0)
	s_bitcmp1_b32 s100, 1
	s_cbranch_scc0 .Lpv1_x
	ds_write_b64 v250, v[208:209]
	ds_write_b64 v251, v[210:211]
	ds_write_b64 v250, v[212:213] offset:2048
	ds_write_b64 v251, v[214:215] offset:2048
	ds_write_b64 v250, v[216:217] offset:4096
	ds_write_b64 v251, v[218:219] offset:4096
	ds_write_b64 v250, v[220:221] offset:6144
	ds_write_b64 v251, v[222:223] offset:6144
.Lpv1_x:
	s_waitcnt lgkmcnt(0)
	s_barrier
	s_lshl_b64 s[28:29], s[28:29], 1
	v_bfe_i32 v2, v10, 27, 1
	v_lshlrev_b32_e32 v0, 4, v10
	v_lshrrev_b32_e32 v2, 22, v2
	v_add_u32_e32 v2, v0, v2
	v_and_b32_e32 v2, 0xfffffc00, v2
	v_sub_u32_e32 v2, v0, v2
	v_lshrrev_b32_e32 v3, 4, v2
	v_bitop3_b32 v2, v3, v2, 32 bitop3:0x6c
	v_ashrrev_i32_e32 v1, 31, v10
	v_ashrrev_i32_e32 v4, 31, v2
	v_lshrrev_b32_e32 v1, 26, v1
	v_lshrrev_b32_e32 v4, 26, v4
	v_add_u32_e32 v1, v10, v1
	v_add_u32_e32 v4, v2, v4
	v_ashrrev_i32_e32 v1, 6, v1
	v_lshrrev_b32_e32 v5, 6, v4
	v_and_b32_e32 v4, 0xc0, v4
	v_lshlrev_b32_e32 v3, 3, v1
	v_lshlrev_b32_e32 v1, 5, v1
	v_sub_u32_e32 v2, v2, v4
	v_and_b32_e32 v3, 0x7ffff0, v3
	v_and_b32_e32 v1, 32, v1
	v_ashrrev_i16_sdwa v2, v133, sext(v2) dst_sel:DWORD dst_unused:UNUSED_PAD src0_sel:DWORD src1_sel:BYTE_0
	v_add_u32_sdwa v1, v1, sext(v2) dst_sel:DWORD dst_unused:UNUSED_PAD src0_sel:DWORD src1_sel:WORD_0
	v_add_lshl_u32 v2, v5, v3, 9
	v_add_u32_e32 v0, 0x2000, v0
	v_lshl_add_u32 v128, v1, 1, v2
	v_ashrrev_i32_e32 v1, 31, v0
	v_lshrrev_b32_e32 v1, 22, v1
	v_add_u32_e32 v1, v0, v1
	v_ashrrev_i32_e32 v1, 10, v1
	v_mul_i32_i24_e32 v2, 0x400, v1
	v_sub_u32_e32 v0, v0, v2
	v_lshrrev_b32_e32 v2, 4, v0
	v_bitop3_b32 v0, v2, v0, 32 bitop3:0x6c
	v_ashrrev_i32_e32 v3, 31, v0
	v_lshrrev_b32_e32 v3, 26, v3
	s_add_u32 s28, s66, s28
	v_readfirstlane_b32 s27, v10
	v_add_u32_e32 v3, v0, v3
	s_addc_u32 s29, s67, s29
	v_lshrrev_b32_e32 v4, 6, v3
	v_and_b32_e32 v3, 0xc0, v3
	s_ashr_i32 s31, s27, 6
	v_lshlrev_b32_e32 v2, 3, v1
	v_lshlrev_b32_e32 v1, 5, v1
	v_sub_u32_e32 v0, v0, v3
	s_lshl_b32 s51, s31, 10
	v_and_b32_e32 v2, 0x7ffff0, v2
	v_and_b32_e32 v1, 32, v1
	v_ashrrev_i16_sdwa v0, v133, sext(v0) dst_sel:DWORD dst_unused:UNUSED_PAD src0_sel:DWORD src1_sel:BYTE_0
	s_add_i32 s73, s51, 0
	v_add_u32_sdwa v0, v1, sext(v0) dst_sel:DWORD dst_unused:UNUSED_PAD src0_sel:DWORD src1_sel:WORD_0
	v_add_lshl_u32 v1, v4, v2, 9
	s_add_i32 m0, s73, 0x10000
	v_lshl_add_u32 v0, v0, 1, v1
	global_load_lds_dwordx4 v128, s[28:29]
	s_add_i32 m0, s73, 0x12000
	s_ashr_i32 s30, s27, 8
	global_load_lds_dwordx4 v0, s[28:29]
	s_mov_b32 m0, s73
	s_add_i32 s74, s73, 0x2000
	s_mov_b32 m0, s74
	s_add_u32 s34, s28, 0x10000
	s_addc_u32 s35, s29, 0
	s_add_i32 m0, s73, 0x14000
	s_add_i32 s33, s73, 0x6000
	global_load_lds_dwordx4 v128, s[34:35]
	s_add_i32 m0, s73, 0x16000
	v_mov_b32_e32 v1, v129
	global_load_lds_dwordx4 v0, s[34:35]
	s_add_i32 s35, s73, 0x4000
	s_mov_b32 m0, s35
	v_lshl_add_u64 v[6:7], s[28:29], 0, v[128:129]
	s_mov_b32 m0, s33
	s_cmp_lg_u32 s30, 1
	v_lshl_add_u64 v[8:9], s[28:29], 0, v[0:1]
	s_cbranch_scc1 .LBB0_1023
	s_barrier
.LBB0_1023:
	v_and_b32_e32 v11, 15, v10
	v_and_b32_e32 v12, 48, v10
	v_lshlrev_b32_e32 v10, 2, v10
	v_lshlrev_b32_e32 v11, 6, v11
	v_and_b32_e32 v10, 32, v10
	s_lshl_b32 s31, s31, 12
	v_or_b32_e32 v13, v11, v12
	v_bitop3_b32 v11, v11, v10, v12 bitop3:0x36
	s_lshl_b32 s30, s30, 13
	s_and_b32 s31, s31, 0x3000
	s_add_i32 s56, s40, s51
	v_or_b32_e32 v12, s31, v11
	v_bitop3_b32 v13, v13, s30, v10 bitop3:0xde
	v_lshl_add_u64 v[10:11], v[6:7], 0, s[20:21]
	s_mov_b32 m0, s56
	s_add_i32 s53, s56, 0x2000
	v_lshl_add_u64 v[4:5], s[0:1], 0, v[128:129]
	s_waitcnt vmcnt(2)
	s_barrier
	global_load_lds_dwordx4 v[10:11], off
	v_lshl_add_u64 v[10:11], v[8:9], 0, s[20:21]
	s_mov_b32 m0, s53
	s_add_i32 s52, s73, 0x8000
	s_add_i32 s34, s73, 0xa000
	v_lshl_add_u64 v[2:3], s[0:1], 0, v[0:1]
	global_load_lds_dwordx4 v[10:11], off
	v_lshl_add_u64 v[10:11], v[4:5], 0, s[20:21]
	s_mov_b32 m0, s52
	s_add_u32 s76, s28, 0x10080
	v_lshl_add_u64 v[10:11], v[2:3], 0, s[20:21]
	s_mov_b32 m0, s34
	s_addc_u32 s77, s29, 0
	s_add_i32 s31, s41, s51
	v_lshl_add_u64 v[10:11], s[76:77], 0, v[128:129]
	s_mov_b32 m0, s31
	s_add_i32 s30, s31, 0x2000
	global_load_lds_dwordx4 v[10:11], off
	v_lshl_add_u64 v[10:11], s[76:77], 0, v[0:1]
	s_mov_b32 m0, s30
	v_add_u32_e32 v134, s43, v12
	global_load_lds_dwordx4 v[10:11], off
	v_add_u32_e32 v11, s42, v12
	s_waitcnt vmcnt(4)
	s_barrier
	v_add_u32_e32 v10, 0, v13
	v_add_u32_e32 v135, s40, v12
	v_add_u32_e32 v184, s41, v12
	ds_read_b128 v[12:15], v11
	ds_read_b128 v[16:19], v11 offset:1024
	ds_read_b128 v[20:23], v11 offset:2048
	ds_read_b128 v[24:27], v11 offset:3072
	s_add_i32 s72, s73, 0xc000
	v_lshl_add_u64 v[60:61], s[14:15], 0, v[128:129]
	s_mov_b32 m0, s72
	s_add_i32 s57, s73, 0xe000
	ds_read_b128 v[28:31], v10
	ds_read_b128 v[32:35], v10 offset:1024
	ds_read_b128 v[36:39], v10 offset:2048
	ds_read_b128 v[40:43], v10 offset:3072
	ds_read_b128 v[44:47], v10 offset:4096
	ds_read_b128 v[48:51], v10 offset:5120
	ds_read_b128 v[52:55], v10 offset:6144
	ds_read_b128 v[56:59], v10 offset:7168
	v_lshl_add_u64 v[60:61], s[14:15], 0, v[0:1]
	s_mov_b32 m0, s57
	s_nop 0
	s_waitcnt lgkmcnt(8)
	s_barrier
	s_waitcnt lgkmcnt(0)
	s_setprio 1
	s_waitcnt lgkmcnt(0)
	v_mfma_f32_16x16x32_bf16 v[60:63], v[12:15], v[28:31], 0
	v_mfma_f32_16x16x32_bf16 v[64:67], v[20:23], v[28:31], 0
	v_mfma_f32_16x16x32_bf16 v[68:71], v[12:15], v[36:39], 0
	v_mfma_f32_16x16x32_bf16 v[72:75], v[20:23], v[36:39], 0
	v_mfma_f32_16x16x32_bf16 v[76:79], v[12:15], v[44:47], 0
	v_mfma_f32_16x16x32_bf16 v[80:83], v[20:23], v[44:47], 0
	v_mfma_f32_16x16x32_bf16 v[84:87], v[12:15], v[52:55], 0
	v_mfma_f32_16x16x32_bf16 v[88:91], v[20:23], v[52:55], 0
	v_mfma_f32_16x16x32_bf16 v[60:63], v[16:19], v[32:35], v[60:63]
	v_mfma_f32_16x16x32_bf16 v[64:67], v[24:27], v[32:35], v[64:67]
	v_mfma_f32_16x16x32_bf16 v[68:71], v[16:19], v[40:43], v[68:71]
	v_mfma_f32_16x16x32_bf16 v[72:75], v[24:27], v[40:43], v[72:75]
	v_mfma_f32_16x16x32_bf16 v[76:79], v[16:19], v[48:51], v[76:79]
	v_mfma_f32_16x16x32_bf16 v[80:83], v[24:27], v[48:51], v[80:83]
	v_mfma_f32_16x16x32_bf16 v[84:87], v[16:19], v[56:59], v[84:87]
	v_mfma_f32_16x16x32_bf16 v[88:91], v[24:27], v[56:59], v[88:91]
	s_setprio 0
	s_barrier
	s_add_i32 s75, s42, s51
	v_lshl_add_u64 v[108:109], v[6:7], 0, s[22:23]
	s_mov_b32 m0, s75
	ds_read_b128 v[92:95], v134
	ds_read_b128 v[96:99], v134 offset:1024
	ds_read_b128 v[100:103], v134 offset:2048
	ds_read_b128 v[104:107], v134 offset:3072
	global_load_lds_dwordx4 v[108:109], off
	v_lshl_add_u64 v[108:109], v[8:9], 0, s[22:23]
	s_add_i32 m0, s75, 0x2000
	s_nop 0
	global_load_lds_dwordx4 v[108:109], off
	s_barrier
	s_waitcnt lgkmcnt(0)
	s_setprio 1
	s_waitcnt lgkmcnt(0)
	v_mfma_f32_16x16x32_bf16 v[108:111], v[92:95], v[28:31], 0
	v_mfma_f32_16x16x32_bf16 v[28:31], v[100:103], v[28:31], 0
	v_mfma_f32_16x16x32_bf16 v[108:111], v[96:99], v[32:35], v[108:111]
	v_mfma_f32_16x16x32_bf16 v[28:31], v[104:107], v[32:35], v[28:31]
	v_mfma_f32_16x16x32_bf16 v[32:35], v[92:95], v[36:39], 0
	v_mfma_f32_16x16x32_bf16 v[36:39], v[100:103], v[36:39], 0
	v_mfma_f32_16x16x32_bf16 v[32:35], v[96:99], v[40:43], v[32:35]
	v_mfma_f32_16x16x32_bf16 v[36:39], v[104:107], v[40:43], v[36:39]
	v_mfma_f32_16x16x32_bf16 v[40:43], v[92:95], v[44:47], 0
	v_mfma_f32_16x16x32_bf16 v[44:47], v[100:103], v[44:47], 0
	v_mfma_f32_16x16x32_bf16 v[40:43], v[96:99], v[48:51], v[40:43]
	v_mfma_f32_16x16x32_bf16 v[44:47], v[104:107], v[48:51], v[44:47]
	v_mfma_f32_16x16x32_bf16 v[48:51], v[92:95], v[52:55], 0
	v_mfma_f32_16x16x32_bf16 v[52:55], v[100:103], v[52:55], 0
	v_mfma_f32_16x16x32_bf16 v[48:51], v[96:99], v[56:59], v[48:51]
	v_mfma_f32_16x16x32_bf16 v[52:55], v[104:107], v[56:59], v[52:55]
	s_setprio 0
	s_mov_b32 m0, s73
	v_lshl_add_u64 v[130:131], v[4:5], 0, s[22:23]
	s_barrier
	ds_read_b128 v[56:59], v10 offset:16384
	ds_read_b128 v[112:115], v10 offset:17408
	ds_read_b128 v[116:119], v10 offset:18432
	ds_read_b128 v[120:123], v10 offset:19456
	ds_read_b128 v[124:127], v10 offset:20480
	ds_read_b128 v[138:141], v10 offset:21504
	ds_read_b128 v[142:145], v10 offset:22528
	ds_read_b128 v[146:149], v10 offset:23552
	s_bitcmp1_b32 s100, 1
	s_cbranch_scc1 .Lpv1_a
	ds_write_b64 v248, v[224:225]
	ds_write_b64 v249, v[226:227]
	ds_write_b64 v248, v[228:229] offset:2048
	ds_write_b64 v249, v[230:231] offset:2048
	ds_write_b64 v248, v[232:233] offset:4096
	ds_write_b64 v249, v[234:235] offset:4096
	ds_write_b64 v248, v[236:237] offset:6144
	ds_write_b64 v249, v[238:239] offset:6144
.Lpv1_a:
	v_lshl_add_u64 v[130:131], v[2:3], 0, s[22:23]
	s_mov_b32 m0, s74
	s_nop 0
	s_barrier
	s_waitcnt lgkmcnt(0)
	s_setprio 1
	s_waitcnt lgkmcnt(0)
	v_mfma_f32_16x16x32_bf16 v[150:153], v[12:15], v[56:59], 0
	v_mfma_f32_16x16x32_bf16 v[158:161], v[12:15], v[116:119], 0
	v_mfma_f32_16x16x32_bf16 v[166:169], v[12:15], v[124:127], 0
	v_mfma_f32_16x16x32_bf16 v[12:15], v[12:15], v[142:145], 0
	v_mfma_f32_16x16x32_bf16 v[150:153], v[16:19], v[112:115], v[150:153]
	v_mfma_f32_16x16x32_bf16 v[158:161], v[16:19], v[120:123], v[158:161]
	v_mfma_f32_16x16x32_bf16 v[166:169], v[16:19], v[138:141], v[166:169]
	v_mfma_f32_16x16x32_bf16 v[12:15], v[16:19], v[146:149], v[12:15]
	v_mfma_f32_16x16x32_bf16 v[16:19], v[20:23], v[142:145], 0
	v_mfma_f32_16x16x32_bf16 v[154:157], v[20:23], v[56:59], 0
	v_mfma_f32_16x16x32_bf16 v[162:165], v[20:23], v[116:119], 0
	v_mfma_f32_16x16x32_bf16 v[170:173], v[20:23], v[124:127], 0
	v_mfma_f32_16x16x32_bf16 v[16:19], v[24:27], v[146:149], v[16:19]
	v_mfma_f32_16x16x32_bf16 v[154:157], v[24:27], v[112:115], v[154:157]
	v_mfma_f32_16x16x32_bf16 v[162:165], v[24:27], v[120:123], v[162:165]
	v_mfma_f32_16x16x32_bf16 v[170:173], v[24:27], v[138:141], v[170:173]
	s_setprio 0
	s_barrier
	s_add_u32 s74, s28, 0x10100
	s_addc_u32 s75, s29, 0
	s_add_i32 s51, s43, s51
	v_lshl_add_u64 v[20:21], s[74:75], 0, v[128:129]
	s_mov_b32 m0, s51
	s_nop 0
	global_load_lds_dwordx4 v[20:21], off
	v_lshl_add_u64 v[20:21], s[74:75], 0, v[0:1]
	s_add_i32 m0, s51, 0x2000
	s_nop 0
	global_load_lds_dwordx4 v[20:21], off
	s_waitcnt vmcnt(4)
	s_barrier
	s_setprio 1
	v_mfma_f32_16x16x32_bf16 v[20:23], v[92:95], v[56:59], 0
	v_mfma_f32_16x16x32_bf16 v[24:27], v[100:103], v[56:59], 0
	v_mfma_f32_16x16x32_bf16 v[20:23], v[96:99], v[112:115], v[20:23]
	v_mfma_f32_16x16x32_bf16 v[24:27], v[104:107], v[112:115], v[24:27]
	v_mfma_f32_16x16x32_bf16 v[56:59], v[92:95], v[116:119], 0
	v_mfma_f32_16x16x32_bf16 v[112:115], v[100:103], v[116:119], 0
	v_mfma_f32_16x16x32_bf16 v[116:119], v[92:95], v[124:127], 0
	v_mfma_f32_16x16x32_bf16 v[92:95], v[92:95], v[142:145], 0
	v_mfma_f32_16x16x32_bf16 v[56:59], v[96:99], v[120:123], v[56:59]
	v_mfma_f32_16x16x32_bf16 v[112:115], v[104:107], v[120:123], v[112:115]
	v_mfma_f32_16x16x32_bf16 v[116:119], v[96:99], v[138:141], v[116:119]
	v_mfma_f32_16x16x32_bf16 v[120:123], v[100:103], v[124:127], 0
	v_mfma_f32_16x16x32_bf16 v[92:95], v[96:99], v[146:149], v[92:95]
	v_mfma_f32_16x16x32_bf16 v[96:99], v[100:103], v[142:145], 0
	v_mfma_f32_16x16x32_bf16 v[120:123], v[104:107], v[138:141], v[120:123]
	v_mfma_f32_16x16x32_bf16 v[96:99], v[104:107], v[146:149], v[96:99]
	s_setprio 0
	s_barrier
	ds_read_b128 v[100:103], v135
	ds_read_b128 v[104:107], v135 offset:1024
	ds_read_b128 v[124:127], v135 offset:2048
	ds_read_b128 v[138:141], v135 offset:3072
	s_mov_b32 m0, s35
	v_lshl_add_u64 v[130:131], s[16:17], 0, v[128:129]
	ds_read_b128 v[142:145], v10 offset:32768
	ds_read_b128 v[146:149], v10 offset:33792
	ds_read_b128 v[174:177], v10 offset:34816
	ds_read_b128 v[178:181], v10 offset:35840
	ds_read_b128 v[192:195], v10 offset:36864
	ds_read_b128 v[196:199], v10 offset:37888
	ds_read_b128 v[200:203], v10 offset:38912
	ds_read_b128 v[204:207], v10 offset:39936
	s_bitcmp1_b32 s100, 1
	s_cbranch_scc1 .Lpv1_b
	ds_write_b64 v248, v[208:209] offset:16384
	ds_write_b64 v249, v[210:211] offset:16384
	ds_write_b64 v248, v[212:213] offset:18432
	ds_write_b64 v249, v[214:215] offset:18432
	ds_write_b64 v248, v[216:217] offset:20480
	ds_write_b64 v249, v[218:219] offset:20480
	ds_write_b64 v248, v[220:221] offset:22528
	ds_write_b64 v249, v[222:223] offset:22528
.Lpv1_b:
	v_lshl_add_u64 v[130:131], s[16:17], 0, v[0:1]
	s_mov_b32 m0, s33
	s_nop 0
	s_waitcnt lgkmcnt(8)
	s_barrier
	s_waitcnt lgkmcnt(0)
	s_setprio 1
	s_waitcnt lgkmcnt(0)
	v_mfma_f32_16x16x32_bf16 v[60:63], v[100:103], v[142:145], v[60:63]
	v_mfma_f32_16x16x32_bf16 v[64:67], v[124:127], v[142:145], v[64:67]
	v_mfma_f32_16x16x32_bf16 v[68:71], v[100:103], v[174:177], v[68:71]
	v_mfma_f32_16x16x32_bf16 v[72:75], v[124:127], v[174:177], v[72:75]
	v_mfma_f32_16x16x32_bf16 v[76:79], v[100:103], v[192:195], v[76:79]
	v_mfma_f32_16x16x32_bf16 v[80:83], v[124:127], v[192:195], v[80:83]
	v_mfma_f32_16x16x32_bf16 v[84:87], v[100:103], v[200:203], v[84:87]
	v_mfma_f32_16x16x32_bf16 v[88:91], v[124:127], v[200:203], v[88:91]
	v_mfma_f32_16x16x32_bf16 v[60:63], v[104:107], v[146:149], v[60:63]
	v_mfma_f32_16x16x32_bf16 v[64:67], v[138:141], v[146:149], v[64:67]
	v_mfma_f32_16x16x32_bf16 v[68:71], v[104:107], v[178:181], v[68:71]
	v_mfma_f32_16x16x32_bf16 v[72:75], v[138:141], v[178:181], v[72:75]
	v_mfma_f32_16x16x32_bf16 v[76:79], v[104:107], v[196:199], v[76:79]
	v_mfma_f32_16x16x32_bf16 v[80:83], v[138:141], v[196:199], v[80:83]
	v_mfma_f32_16x16x32_bf16 v[84:87], v[104:107], v[204:207], v[84:87]
	v_mfma_f32_16x16x32_bf16 v[88:91], v[138:141], v[204:207], v[88:91]
	s_setprio 0
	s_barrier
	s_mov_b32 m0, s56
	v_lshl_add_u64 v[6:7], v[6:7], 0, s[24:25]
	ds_read_b128 v[208:211], v184
	ds_read_b128 v[212:215], v184 offset:1024
	ds_read_b128 v[216:219], v184 offset:2048
	ds_read_b128 v[220:223], v184 offset:3072
	global_load_lds_dwordx4 v[6:7], off
	v_lshl_add_u64 v[6:7], v[8:9], 0, s[24:25]
	s_mov_b32 m0, s53
	s_nop 0
	global_load_lds_dwordx4 v[6:7], off
	s_barrier
	s_waitcnt lgkmcnt(0)
	s_setprio 1
	s_waitcnt lgkmcnt(0)
	v_mfma_f32_16x16x32_bf16 v[6:9], v[208:211], v[142:145], v[108:111]
	v_mfma_f32_16x16x32_bf16 v[28:31], v[216:219], v[142:145], v[28:31]
	v_mfma_f32_16x16x32_bf16 v[32:35], v[208:211], v[174:177], v[32:35]
	v_mfma_f32_16x16x32_bf16 v[36:39], v[216:219], v[174:177], v[36:39]
	v_mfma_f32_16x16x32_bf16 v[40:43], v[208:211], v[192:195], v[40:43]
	v_mfma_f32_16x16x32_bf16 v[44:47], v[216:219], v[192:195], v[44:47]
	v_mfma_f32_16x16x32_bf16 v[48:51], v[208:211], v[200:203], v[48:51]
	v_mfma_f32_16x16x32_bf16 v[52:55], v[216:219], v[200:203], v[52:55]
	v_mfma_f32_16x16x32_bf16 v[6:9], v[212:215], v[146:149], v[6:9]
	v_mfma_f32_16x16x32_bf16 v[28:31], v[220:223], v[146:149], v[28:31]
	v_mfma_f32_16x16x32_bf16 v[32:35], v[212:215], v[178:181], v[32:35]
	v_mfma_f32_16x16x32_bf16 v[36:39], v[220:223], v[178:181], v[36:39]
	v_mfma_f32_16x16x32_bf16 v[40:43], v[212:215], v[196:199], v[40:43]
	v_mfma_f32_16x16x32_bf16 v[44:47], v[220:223], v[196:199], v[44:47]
	v_mfma_f32_16x16x32_bf16 v[48:51], v[212:215], v[204:207], v[48:51]
	v_mfma_f32_16x16x32_bf16 v[52:55], v[220:223], v[204:207], v[52:55]
	s_setprio 0
	s_mov_b32 m0, s52
	v_lshl_add_u64 v[4:5], v[4:5], 0, s[24:25]
	s_barrier
	ds_read_b128 v[108:111], v10 offset:49152
	ds_read_b128 v[142:145], v10 offset:50176
	ds_read_b128 v[146:149], v10 offset:51200
	ds_read_b128 v[174:177], v10 offset:52224
	ds_read_b128 v[178:181], v10 offset:53248
	ds_read_b128 v[192:195], v10 offset:54272
	ds_read_b128 v[196:199], v10 offset:55296
	ds_read_b128 v[200:203], v10 offset:56320
	s_bitcmp1_b32 s100, 1
	s_cbranch_scc0 .Lpv1_c
	ds_write_b64 v248, v[224:225]
	ds_write_b64 v249, v[226:227]
	ds_write_b64 v248, v[228:229] offset:2048
	ds_write_b64 v249, v[230:231] offset:2048
	ds_write_b64 v248, v[232:233] offset:4096
	ds_write_b64 v249, v[234:235] offset:4096
	ds_write_b64 v248, v[236:237] offset:6144
	ds_write_b64 v249, v[238:239] offset:6144
.Lpv1_c:
	v_lshl_add_u64 v[2:3], v[2:3], 0, s[24:25]
	s_mov_b32 m0, s34
	s_nop 0
	s_barrier
	s_waitcnt lgkmcnt(0)
	s_setprio 1
	s_waitcnt lgkmcnt(0)
	v_mfma_f32_16x16x32_bf16 v[2:5], v[100:103], v[108:111], v[150:153]
	v_mfma_f32_16x16x32_bf16 v[12:15], v[100:103], v[196:199], v[12:15]
	v_mfma_f32_16x16x32_bf16 v[16:19], v[124:127], v[196:199], v[16:19]
	v_mfma_f32_16x16x32_bf16 v[2:5], v[104:107], v[142:145], v[2:5]
	v_mfma_f32_16x16x32_bf16 v[150:153], v[124:127], v[108:111], v[154:157]
	v_mfma_f32_16x16x32_bf16 v[154:157], v[100:103], v[146:149], v[158:161]
	v_mfma_f32_16x16x32_bf16 v[158:161], v[124:127], v[146:149], v[162:165]
	v_mfma_f32_16x16x32_bf16 v[162:165], v[100:103], v[178:181], v[166:169]
	v_mfma_f32_16x16x32_bf16 v[166:169], v[124:127], v[178:181], v[170:173]
	v_mfma_f32_16x16x32_bf16 v[12:15], v[104:107], v[200:203], v[12:15]
	v_mfma_f32_16x16x32_bf16 v[16:19], v[138:141], v[200:203], v[16:19]
	v_mfma_f32_16x16x32_bf16 v[150:153], v[138:141], v[142:145], v[150:153]
	v_mfma_f32_16x16x32_bf16 v[154:157], v[104:107], v[174:177], v[154:157]
	v_mfma_f32_16x16x32_bf16 v[158:161], v[138:141], v[174:177], v[158:161]
	v_mfma_f32_16x16x32_bf16 v[162:165], v[104:107], v[192:195], v[162:165]
	v_mfma_f32_16x16x32_bf16 v[166:169], v[138:141], v[192:195], v[166:169]
	s_setprio 0
	s_barrier
	s_add_u32 s28, s28, 0x10180
	s_addc_u32 s29, s29, 0
	s_mov_b32 m0, s31
	v_lshl_add_u64 v[100:101], s[28:29], 0, v[128:129]
	global_load_lds_dwordx4 v[100:101], off
	v_lshl_add_u64 v[100:101], s[28:29], 0, v[0:1]
	s_mov_b32 m0, s30
	s_nop 0
	global_load_lds_dwordx4 v[100:101], off
	s_waitcnt vmcnt(4)
	s_barrier
	s_setprio 1
	v_mfma_f32_16x16x32_bf16 v[20:23], v[208:211], v[108:111], v[20:23]
	v_mfma_f32_16x16x32_bf16 v[24:27], v[216:219], v[108:111], v[24:27]
	v_mfma_f32_16x16x32_bf16 v[56:59], v[208:211], v[146:149], v[56:59]
	v_mfma_f32_16x16x32_bf16 v[100:103], v[216:219], v[146:149], v[112:115]
	v_mfma_f32_16x16x32_bf16 v[104:107], v[208:211], v[178:181], v[116:119]
	v_mfma_f32_16x16x32_bf16 v[108:111], v[216:219], v[178:181], v[120:123]
	v_mfma_f32_16x16x32_bf16 v[92:95], v[208:211], v[196:199], v[92:95]
	v_mfma_f32_16x16x32_bf16 v[96:99], v[216:219], v[196:199], v[96:99]
	v_mfma_f32_16x16x32_bf16 v[20:23], v[212:215], v[142:145], v[20:23]
	v_mfma_f32_16x16x32_bf16 v[24:27], v[220:223], v[142:145], v[24:27]
	v_mfma_f32_16x16x32_bf16 v[56:59], v[212:215], v[174:177], v[56:59]
	v_mfma_f32_16x16x32_bf16 v[100:103], v[220:223], v[174:177], v[100:103]
	v_mfma_f32_16x16x32_bf16 v[104:107], v[212:215], v[192:195], v[104:107]
	v_mfma_f32_16x16x32_bf16 v[108:111], v[220:223], v[192:195], v[108:111]
	v_mfma_f32_16x16x32_bf16 v[92:95], v[212:215], v[200:203], v[92:95]
	v_mfma_f32_16x16x32_bf16 v[96:99], v[220:223], v[200:203], v[96:99]
	s_setprio 0
	s_mov_b32 m0, s72
	v_lshl_add_u64 v[130:131], s[18:19], 0, v[128:129]
	s_barrier
	ds_read_b128 v[112:115], v11
	ds_read_b128 v[116:119], v11 offset:1024
	ds_read_b128 v[120:123], v11 offset:2048
	ds_read_b128 v[124:127], v11 offset:3072
	ds_read_b128 v[138:141], v10
	ds_read_b128 v[142:145], v10 offset:1024
	ds_read_b128 v[146:149], v10 offset:2048
	ds_read_b128 v[170:173], v10 offset:3072
	ds_read_b128 v[174:177], v10 offset:4096
	ds_read_b128 v[178:181], v10 offset:5120
	ds_read_b128 v[192:195], v10 offset:6144
	ds_read_b128 v[196:199], v10 offset:7168
	v_lshl_add_u64 v[0:1], s[18:19], 0, v[0:1]
	s_mov_b32 m0, s57
	s_nop 0
	s_barrier
	s_waitcnt lgkmcnt(0)
	s_setprio 1
	s_waitcnt lgkmcnt(0)
	v_mfma_f32_16x16x32_bf16 v[84:87], v[112:115], v[192:195], v[84:87]
	v_mfma_f32_16x16x32_bf16 v[60:63], v[112:115], v[138:141], v[60:63]
	v_mfma_f32_16x16x32_bf16 v[64:67], v[120:123], v[138:141], v[64:67]
	v_mfma_f32_16x16x32_bf16 v[68:71], v[112:115], v[146:149], v[68:71]
	v_mfma_f32_16x16x32_bf16 v[72:75], v[120:123], v[146:149], v[72:75]
	v_mfma_f32_16x16x32_bf16 v[76:79], v[112:115], v[174:177], v[76:79]
	v_mfma_f32_16x16x32_bf16 v[80:83], v[120:123], v[174:177], v[80:83]
	v_mfma_f32_16x16x32_bf16 v[200:203], v[116:119], v[196:199], v[84:87]
	v_mfma_f32_16x16x32_bf16 v[84:87], v[120:123], v[192:195], v[88:91]
	v_mfma_f32_16x16x32_bf16 v[60:63], v[116:119], v[142:145], v[60:63]
	v_mfma_f32_16x16x32_bf16 v[64:67], v[124:127], v[142:145], v[64:67]
	v_mfma_f32_16x16x32_bf16 v[68:71], v[116:119], v[170:173], v[68:71]
	v_mfma_f32_16x16x32_bf16 v[72:75], v[124:127], v[170:173], v[72:75]
	v_mfma_f32_16x16x32_bf16 v[76:79], v[116:119], v[178:181], v[76:79]
	v_mfma_f32_16x16x32_bf16 v[80:83], v[124:127], v[178:181], v[80:83]
	v_mfma_f32_16x16x32_bf16 v[88:91], v[124:127], v[196:199], v[84:87]
	s_setprio 0
	s_barrier
	s_nop 0
	ds_read_b128 v[84:87], v134
	ds_read_b128 v[204:207], v134 offset:1024
	ds_read_b128 v[208:211], v134 offset:2048
	ds_read_b128 v[212:215], v134 offset:3072
	s_barrier
	s_waitcnt lgkmcnt(0)
	s_setprio 1
	s_waitcnt lgkmcnt(0)
	v_mfma_f32_16x16x32_bf16 v[6:9], v[84:87], v[138:141], v[6:9]
	v_mfma_f32_16x16x32_bf16 v[28:31], v[208:211], v[138:141], v[28:31]
	v_mfma_f32_16x16x32_bf16 v[32:35], v[84:87], v[146:149], v[32:35]
	v_mfma_f32_16x16x32_bf16 v[36:39], v[208:211], v[146:149], v[36:39]
	v_mfma_f32_16x16x32_bf16 v[40:43], v[84:87], v[174:177], v[40:43]
	v_mfma_f32_16x16x32_bf16 v[44:47], v[208:211], v[174:177], v[44:47]
	v_mfma_f32_16x16x32_bf16 v[48:51], v[84:87], v[192:195], v[48:51]
	v_mfma_f32_16x16x32_bf16 v[6:9], v[204:207], v[142:145], v[6:9]
	v_mfma_f32_16x16x32_bf16 v[28:31], v[212:215], v[142:145], v[28:31]
	v_mfma_f32_16x16x32_bf16 v[32:35], v[204:207], v[170:173], v[32:35]
	v_mfma_f32_16x16x32_bf16 v[36:39], v[212:215], v[170:173], v[36:39]
	v_mfma_f32_16x16x32_bf16 v[40:43], v[204:207], v[178:181], v[40:43]
	v_mfma_f32_16x16x32_bf16 v[44:47], v[212:215], v[178:181], v[44:47]
	v_mfma_f32_16x16x32_bf16 v[48:51], v[204:207], v[196:199], v[48:51]
	v_mfma_f32_16x16x32_bf16 v[52:55], v[208:211], v[192:195], v[52:55]
	v_mfma_f32_16x16x32_bf16 v[138:141], v[212:215], v[196:199], v[52:55]
	s_setprio 0
	s_barrier
	s_nop 4
	ds_read_b128 v[52:55], v10 offset:16384
	ds_read_b128 v[142:145], v10 offset:17408
	ds_read_b128 v[146:149], v10 offset:18432
	ds_read_b128 v[170:173], v10 offset:19456
	ds_read_b128 v[174:177], v10 offset:20480
	ds_read_b128 v[178:181], v10 offset:21504
	ds_read_b128 v[192:195], v10 offset:22528
	ds_read_b128 v[196:199], v10 offset:23552
	s_waitcnt vmcnt(2)
	s_barrier
	s_waitcnt lgkmcnt(0)
	s_setprio 1
	s_waitcnt lgkmcnt(0)
	v_mfma_f32_16x16x32_bf16 v[0:3], v[112:115], v[52:55], v[2:5]
	v_mfma_f32_16x16x32_bf16 v[12:15], v[112:115], v[192:195], v[12:15]
	v_mfma_f32_16x16x32_bf16 v[0:3], v[116:119], v[142:145], v[0:3]
	v_mfma_f32_16x16x32_bf16 v[150:153], v[120:123], v[52:55], v[150:153]
	v_mfma_f32_16x16x32_bf16 v[154:157], v[112:115], v[146:149], v[154:157]
	v_mfma_f32_16x16x32_bf16 v[158:161], v[120:123], v[146:149], v[158:161]
	v_mfma_f32_16x16x32_bf16 v[162:165], v[112:115], v[174:177], v[162:165]
	v_mfma_f32_16x16x32_bf16 v[166:169], v[120:123], v[174:177], v[166:169]
	v_mfma_f32_16x16x32_bf16 v[12:15], v[116:119], v[196:199], v[12:15]
	v_mfma_f32_16x16x32_bf16 v[16:19], v[120:123], v[192:195], v[16:19]
	v_mfma_f32_16x16x32_bf16 v[150:153], v[124:127], v[142:145], v[150:153]
	v_mfma_f32_16x16x32_bf16 v[154:157], v[116:119], v[170:173], v[154:157]
	v_mfma_f32_16x16x32_bf16 v[158:161], v[124:127], v[170:173], v[158:161]
	v_mfma_f32_16x16x32_bf16 v[162:165], v[116:119], v[178:181], v[162:165]
	v_mfma_f32_16x16x32_bf16 v[166:169], v[124:127], v[178:181], v[166:169]
	v_mfma_f32_16x16x32_bf16 v[216:219], v[124:127], v[196:199], v[16:19]
	s_setprio 0
	s_setprio 1
	v_mfma_f32_16x16x32_bf16 v[16:19], v[84:87], v[52:55], v[20:23]
	v_mfma_f32_16x16x32_bf16 v[20:23], v[204:207], v[142:145], v[16:19]
	v_mfma_f32_16x16x32_bf16 v[16:19], v[208:211], v[52:55], v[24:27]
	v_mfma_f32_16x16x32_bf16 v[142:145], v[212:215], v[142:145], v[16:19]
	v_mfma_f32_16x16x32_bf16 v[16:19], v[84:87], v[146:149], v[56:59]
	v_mfma_f32_16x16x32_bf16 v[220:223], v[204:207], v[170:173], v[16:19]
	v_mfma_f32_16x16x32_bf16 v[16:19], v[208:211], v[146:149], v[100:103]
	v_mfma_f32_16x16x32_bf16 v[146:149], v[212:215], v[170:173], v[16:19]
	v_mfma_f32_16x16x32_bf16 v[16:19], v[84:87], v[174:177], v[104:107]
	v_mfma_f32_16x16x32_bf16 v[170:173], v[204:207], v[178:181], v[16:19]
	v_mfma_f32_16x16x32_bf16 v[16:19], v[208:211], v[174:177], v[108:111]
	v_mfma_f32_16x16x32_bf16 v[174:177], v[212:215], v[178:181], v[16:19]
	v_mfma_f32_16x16x32_bf16 v[16:19], v[84:87], v[192:195], v[92:95]
	v_mfma_f32_16x16x32_bf16 v[178:181], v[204:207], v[196:199], v[16:19]
	v_mfma_f32_16x16x32_bf16 v[16:19], v[208:211], v[192:195], v[96:99]
	v_mfma_f32_16x16x32_bf16 v[192:195], v[212:215], v[196:199], v[16:19]
	s_setprio 0
	s_barrier
	ds_read_b128 v[56:59], v135
	ds_read_b128 v[196:199], v135 offset:1024
	ds_read_b128 v[204:207], v135 offset:2048
	ds_read_b128 v[208:211], v135 offset:3072
	s_nop 0
	ds_read_b128 v[16:19], v10 offset:32768
	ds_read_b128 v[24:27], v10 offset:33792
	ds_read_b128 v[92:95], v10 offset:34816
	ds_read_b128 v[104:107], v10 offset:35840
	ds_read_b128 v[212:215], v10 offset:36864
	ds_read_b128 v[224:227], v10 offset:37888
	ds_read_b128 v[228:231], v10 offset:38912
	ds_read_b128 v[232:235], v10 offset:39936
	s_waitcnt vmcnt(0)
	s_barrier
	s_waitcnt lgkmcnt(0)
	s_setprio 1
	s_waitcnt lgkmcnt(0)
	v_mfma_f32_16x16x32_bf16 v[52:55], v[56:59], v[16:19], v[60:63]
	v_mfma_f32_16x16x32_bf16 v[116:119], v[196:199], v[24:27], v[52:55]
	v_mfma_f32_16x16x32_bf16 v[52:55], v[204:207], v[16:19], v[64:67]
	v_mfma_f32_16x16x32_bf16 v[112:115], v[208:211], v[24:27], v[52:55]
	v_mfma_f32_16x16x32_bf16 v[52:55], v[56:59], v[92:95], v[68:71]
	v_mfma_f32_16x16x32_bf16 v[100:103], v[196:199], v[104:107], v[52:55]
	v_mfma_f32_16x16x32_bf16 v[52:55], v[204:207], v[92:95], v[72:75]
	v_mfma_f32_16x16x32_bf16 v[96:99], v[208:211], v[104:107], v[52:55]
	v_mfma_f32_16x16x32_bf16 v[52:55], v[56:59], v[212:215], v[76:79]
	v_mfma_f32_16x16x32_bf16 v[84:87], v[196:199], v[224:227], v[52:55]
	v_mfma_f32_16x16x32_bf16 v[52:55], v[204:207], v[212:215], v[80:83]
	v_mfma_f32_16x16x32_bf16 v[80:83], v[208:211], v[224:227], v[52:55]
	v_mfma_f32_16x16x32_bf16 v[52:55], v[56:59], v[228:231], v[200:203]
	v_mfma_f32_16x16x32_bf16 v[64:67], v[196:199], v[232:235], v[52:55]
	v_mfma_f32_16x16x32_bf16 v[52:55], v[204:207], v[228:231], v[88:91]
	v_mfma_f32_16x16x32_bf16 v[52:55], v[208:211], v[232:235], v[52:55]
	s_setprio 0
	s_barrier
	ds_read_b128 v[200:203], v184
	ds_read_b128 v[236:239], v184 offset:1024
	ds_read_b128 v[240:243], v184 offset:2048
	ds_read_b128 v[244:247], v184 offset:3072
	s_waitcnt vmcnt(0)
	s_barrier
	s_waitcnt lgkmcnt(0)
	s_setprio 1
	s_waitcnt lgkmcnt(0)
	v_mfma_f32_16x16x32_bf16 v[4:7], v[200:203], v[16:19], v[6:9]
	v_mfma_f32_16x16x32_bf16 v[124:127], v[236:239], v[24:27], v[4:7]
	v_mfma_f32_16x16x32_bf16 v[4:7], v[240:243], v[16:19], v[28:31]
	v_mfma_f32_16x16x32_bf16 v[120:123], v[244:247], v[24:27], v[4:7]
	v_mfma_f32_16x16x32_bf16 v[4:7], v[200:203], v[92:95], v[32:35]
	v_mfma_f32_16x16x32_bf16 v[108:111], v[236:239], v[104:107], v[4:7]
	v_mfma_f32_16x16x32_bf16 v[4:7], v[240:243], v[92:95], v[36:39]
	v_mfma_f32_16x16x32_bf16 v[104:107], v[244:247], v[104:107], v[4:7]
	v_mfma_f32_16x16x32_bf16 v[4:7], v[200:203], v[212:215], v[40:43]
	v_mfma_f32_16x16x32_bf16 v[92:95], v[236:239], v[224:227], v[4:7]
	v_mfma_f32_16x16x32_bf16 v[4:7], v[240:243], v[212:215], v[44:47]
	v_mfma_f32_16x16x32_bf16 v[88:91], v[244:247], v[224:227], v[4:7]
	v_mfma_f32_16x16x32_bf16 v[4:7], v[200:203], v[228:231], v[48:51]
	v_mfma_f32_16x16x32_bf16 v[76:79], v[236:239], v[232:235], v[4:7]
	v_mfma_f32_16x16x32_bf16 v[4:7], v[240:243], v[228:231], v[138:141]
	v_mfma_f32_16x16x32_bf16 v[68:71], v[244:247], v[232:235], v[4:7]
	s_setprio 0
	s_barrier
	s_nop 4
	v_add_u32_e32 v10, 0x16000, v10
	ds_read_b128 v[4:7], v10 offset:49152
	ds_read_b128 v[28:31], v10 offset:50176
	ds_read_b128 v[36:39], v10 offset:51200
	ds_read_b128 v[138:141], v10 offset:52224
	ds_read_b128 v[212:215], v10 offset:53248
	ds_read_b128 v[224:227], v10 offset:54272
	ds_read_b128 v[228:231], v10 offset:55296
	ds_read_b128 v[232:235], v10 offset:56320
	s_barrier
	s_waitcnt lgkmcnt(0)
	s_setprio 1
	s_waitcnt lgkmcnt(0)
	v_mfma_f32_16x16x32_bf16 v[0:3], v[56:59], v[4:7], v[0:3]
	v_mfma_f32_16x16x32_bf16 v[60:63], v[196:199], v[28:31], v[0:3]
	v_mfma_f32_16x16x32_bf16 v[0:3], v[204:207], v[4:7], v[150:153]
	v_mfma_f32_16x16x32_bf16 v[48:51], v[208:211], v[28:31], v[0:3]
	v_mfma_f32_16x16x32_bf16 v[0:3], v[56:59], v[36:39], v[154:157]
	v_mfma_f32_16x16x32_bf16 v[40:43], v[196:199], v[138:141], v[0:3]
	v_mfma_f32_16x16x32_bf16 v[0:3], v[204:207], v[36:39], v[158:161]
	v_mfma_f32_16x16x32_bf16 v[32:35], v[208:211], v[138:141], v[0:3]
	v_mfma_f32_16x16x32_bf16 v[0:3], v[56:59], v[212:215], v[162:165]
	v_mfma_f32_16x16x32_bf16 v[24:27], v[196:199], v[224:227], v[0:3]
	v_mfma_f32_16x16x32_bf16 v[0:3], v[204:207], v[212:215], v[166:169]
	v_mfma_f32_16x16x32_bf16 v[16:19], v[208:211], v[224:227], v[0:3]
	v_mfma_f32_16x16x32_bf16 v[0:3], v[56:59], v[228:231], v[12:15]
	v_mfma_f32_16x16x32_bf16 v[8:11], v[196:199], v[232:235], v[0:3]
	v_mfma_f32_16x16x32_bf16 v[0:3], v[204:207], v[228:231], v[216:219]
	v_mfma_f32_16x16x32_bf16 v[0:3], v[208:211], v[232:235], v[0:3]
	s_setprio 0
	s_setprio 1
	v_mfma_f32_16x16x32_bf16 v[12:15], v[200:203], v[4:7], v[20:23]
	v_mfma_f32_16x16x32_bf16 v[4:7], v[240:243], v[4:7], v[142:145]
	v_mfma_f32_16x16x32_bf16 v[56:59], v[244:247], v[28:31], v[4:7]
	v_mfma_f32_16x16x32_bf16 v[4:7], v[200:203], v[36:39], v[220:223]
	v_mfma_f32_16x16x32_bf16 v[44:47], v[236:239], v[138:141], v[4:7]
	v_mfma_f32_16x16x32_bf16 v[4:7], v[240:243], v[36:39], v[146:149]
	v_mfma_f32_16x16x32_bf16 v[36:39], v[244:247], v[138:141], v[4:7]
	v_mfma_f32_16x16x32_bf16 v[4:7], v[200:203], v[212:215], v[170:173]
	v_mfma_f32_16x16x32_bf16 v[72:75], v[236:239], v[28:31], v[12:15]
	v_mfma_f32_16x16x32_bf16 v[28:31], v[236:239], v[224:227], v[4:7]
	v_mfma_f32_16x16x32_bf16 v[4:7], v[240:243], v[212:215], v[174:177]
	v_mfma_f32_16x16x32_bf16 v[20:23], v[244:247], v[224:227], v[4:7]
	v_mfma_f32_16x16x32_bf16 v[4:7], v[200:203], v[228:231], v[178:181]
	v_mfma_f32_16x16x32_bf16 v[12:15], v[236:239], v[232:235], v[4:7]
	v_mfma_f32_16x16x32_bf16 v[4:7], v[240:243], v[228:231], v[192:195]
	v_mfma_f32_16x16x32_bf16 v[4:7], v[244:247], v[232:235], v[4:7]
	s_setprio 0
	s_cmpk_gt_u32 s27, 0xff
	s_barrier
	s_cbranch_scc1 .LBB0_984
	s_barrier
	s_branch .LBB0_984

.LBB0_1067:
	s_mov_b32 s99, 0x20400
	v_mov_b32_e32 v14, v136
	s_waitcnt vmcnt(0)
	s_barrier
	s_ashr_i32 s33, s51, 5
	v_bfe_i32 v2, v14, 27, 1
	v_lshlrev_b32_e32 v1, 4, v14
	v_lshrrev_b32_e32 v2, 22, v2
	v_add_u32_e32 v2, v1, v2
	v_and_b32_e32 v2, 0xfffffc00, v2
	v_sub_u32_e32 v2, v1, v2
	v_lshrrev_b32_e32 v3, 4, v2
	v_ashrrev_i32_e32 v0, 31, v14
	v_bitop3_b32 v2, v3, v2, 32 bitop3:0x6c
	v_lshrrev_b32_e32 v0, 26, v0
	v_ashrrev_i32_e32 v4, 31, v2
	v_add_u32_e32 v0, v14, v0
	v_lshrrev_b32_e32 v4, 26, v4
	v_ashrrev_i32_e32 v0, 6, v0
	v_add_u32_e32 v4, v2, v4
	v_lshlrev_b32_e32 v3, 3, v0
	v_ashrrev_i32_e32 v5, 6, v4
	v_and_b32_e32 v4, 0xc0, v4
	v_and_b32_e32 v3, -16, v3
	v_lshlrev_b32_e32 v0, 5, v0
	v_sub_u32_e32 v2, v2, v4
	v_add_u32_e32 v3, v5, v3
	v_and_b32_e32 v0, 32, v0
	v_ashrrev_i16_sdwa v2, v133, sext(v2) dst_sel:DWORD dst_unused:UNUSED_PAD src0_sel:DWORD src1_sel:BYTE_0
	v_add_u32_sdwa v0, v0, sext(v2) dst_sel:DWORD dst_unused:UNUSED_PAD src0_sel:DWORD src1_sel:WORD_0
	v_lshlrev_b32_e32 v2, 11, v3
	v_lshl_add_u32 v0, v0, 1, v2
	v_mad_u64_u32 v[6:7], s[56:57], v3, s37, v[0:1]
	v_add_u32_e32 v1, 0x2000, v1
	v_ashrrev_i32_e32 v2, 31, v1
	v_lshrrev_b32_e32 v2, 22, v2
	v_add_u32_e32 v2, v1, v2
	v_ashrrev_i32_e32 v2, 10, v2
	s_lshl_b32 s28, s33, 11
	s_and_b32 s29, s3, 0x700
	v_mul_i32_i24_e32 v3, 0x400, v2
	s_or_b32 s28, s28, s29
	v_sub_u32_e32 v1, v1, v3
	s_ashr_i32 s29, s28, 31
	v_lshrrev_b32_e32 v3, 4, v1
	s_bfe_u32 s52, s51, 0x20003
	s_lshl_b64 s[30:31], s[28:29], 11
	v_bitop3_b32 v1, v3, v1, 32 bitop3:0x6c
	s_add_u32 s29, s62, s30
	v_ashrrev_i32_e32 v4, 31, v1
	s_addc_u32 s30, s63, s31
	s_lshl_b32 s31, s52, 9
	v_lshrrev_b32_e32 v4, 26, v4
	s_add_u32 s34, s29, s31
	v_add_u32_e32 v4, v1, v4
	s_addc_u32 s35, s30, 0
	s_lshl_b32 s29, s33, 2
	v_lshlrev_b32_e32 v3, 3, v2
	v_ashrrev_i32_e32 v5, 6, v4
	v_and_b32_e32 v4, 0xc0, v4
	s_or_b32 s30, s29, s52
	v_and_b32_e32 v3, -16, v3
	v_lshlrev_b32_e32 v2, 5, v2
	v_sub_u32_e32 v1, v1, v4
	s_ashr_i32 s31, s30, 31
	v_add_u32_e32 v3, v5, v3
	v_and_b32_e32 v2, 32, v2
	v_ashrrev_i16_sdwa v1, v133, sext(v1) dst_sel:DWORD dst_unused:UNUSED_PAD src0_sel:DWORD src1_sel:BYTE_0
	s_lshl_b64 s[40:41], s[30:31], 17
	v_add_u32_sdwa v1, v2, sext(v1) dst_sel:DWORD dst_unused:UNUSED_PAD src0_sel:DWORD src1_sel:WORD_0
	v_lshlrev_b32_e32 v2, 11, v3
	s_add_u32 s40, s64, s40
	v_readfirstlane_b32 s29, v14
	v_lshl_add_u32 v2, v1, 1, v2
	s_addc_u32 s41, s65, s41
	v_mad_u64_u32 v[4:5], s[56:57], v3, s37, v[2:3]
	s_ashr_i32 s53, s29, 6
	s_lshl_b32 s57, s53, 10
	s_add_i32 s76, s57, 0
	s_add_i32 m0, s76, 0x10000
	s_ashr_i32 s33, s29, 8
	global_load_lds_dwordx4 v6, s[40:41]
	s_add_i32 m0, s76, 0x12000
	s_add_i32 s77, s76, 0x2000
	global_load_lds_dwordx4 v4, s[40:41]
	s_mov_b32 m0, s76
	s_add_u32 s68, s40, 0x10000
	global_load_lds_dwordx4 v0, s[34:35]
	s_mov_b32 m0, s77
	s_addc_u32 s69, s41, 0
	global_load_lds_dwordx4 v2, s[34:35]
	s_add_i32 m0, s76, 0x14000
	v_mov_b32_e32 v128, v6
	global_load_lds_dwordx4 v6, s[68:69]
	s_add_i32 m0, s76, 0x16000
	s_add_u32 s72, s34, 0x40000
	global_load_lds_dwordx4 v4, s[68:69]
	s_addc_u32 s73, s35, 0
	s_add_i32 s69, s76, 0x4000
	s_mov_b32 m0, s69
	s_add_i32 s56, s76, 0x6000
	global_load_lds_dwordx4 v0, s[72:73]
	s_mov_b32 m0, s56
	v_mov_b32_e32 v5, v129
	global_load_lds_dwordx4 v2, s[72:73]
	v_mov_b32_e32 v1, v129
	v_mov_b32_e32 v3, v129
	v_lshl_add_u64 v[12:13], s[40:41], 0, v[128:129]
	v_lshl_add_u64 v[10:11], s[40:41], 0, v[4:5]
	v_lshl_add_u64 v[6:7], s[34:35], 0, v[0:1]
	s_cmp_lg_u32 s33, 1
	v_lshl_add_u64 v[8:9], s[34:35], 0, v[2:3]
	s_cbranch_scc1 .LBB0_1069
	s_barrier

.LBB0_1071:
	v_max3_f32 v134, v124, s50, v125
	v_max3_f32 v134, v134, v126, v127
	v_max3_f32 v134, v134, v116, v117
	v_and_b32_e32 v131, 64, v137
	v_max3_f32 v134, v134, v118, v119
	v_xor_b32_e32 v130, 16, v137
	v_add_u32_e32 v131, 64, v131
	v_max3_f32 v134, v134, v120, v121
	v_cmp_lt_i32_e32 vcc, v130, v131
	v_max3_f32 v134, v134, v122, v123
	v_max3_f32 v134, v134, v112, v113
	v_cndmask_b32_e32 v130, v137, v130, vcc
	v_lshlrev_b32_e32 v171, 2, v130
	v_max3_f32 v134, v134, v114, v115
	ds_bpermute_b32 v135, v171, v134
	v_xor_b32_e32 v130, 32, v137
	v_cmp_lt_i32_e32 vcc, v130, v131
	v_mov_b32_e32 v169, v136
	s_nop 0
	v_cndmask_b32_e32 v130, v137, v130, vcc
	v_lshlrev_b32_e32 v172, 2, v130
	s_waitcnt lgkmcnt(0)
	v_max_f32_e32 v130, v135, v135
	v_max_f32_e32 v134, v134, v130
	ds_bpermute_b32 v135, v172, v134
	v_bfe_u32 v128, v169, 6, 2
	v_and_b32_e32 v170, 15, v169
	v_bfe_u32 v168, v169, 4, 2
	v_lshl_add_u32 v138, v128, 10, s99
	v_and_b32_e32 v130, 0xffffff00, v169
	v_lshlrev_b32_e32 v131, 2, v170
	v_cmp_eq_u32_e32 vcc, 0, v168
	v_add3_u32 v173, v138, v130, v131
	s_and_saveexec_b64 s[34:35], vcc
	s_cbranch_execz .LBB0_1073
	s_waitcnt lgkmcnt(0)
	v_max_f32_e32 v135, v135, v135
	v_max_f32_e32 v134, v134, v134
	v_max_f32_e32 v134, v134, v135
	ds_write_b32 v173, v134

.LBB0_1087:
	s_or_b64 exec, exec, s[34:35]
	v_add3_u32 v134, s99, v130, v131
	v_add_u32_e32 v142, 0xc00, v134
	s_waitcnt vmcnt(0) lgkmcnt(0)
	s_barrier
	ds_read2_b32 v[160:161], v134 offset1:16
	v_add_u32_e32 v140, 0x800, v134
	ds_read2_b32 v[166:167], v142 offset1:16
	ds_read2_b32 v[164:165], v140 offset1:16
	v_add_u32_e32 v138, 0x400, v134
	ds_read2_b32 v[162:163], v138 offset1:16
	ds_read2_b32 v[152:153], v134 offset0:32 offset1:48
	ds_read2_b32 v[154:155], v138 offset0:32 offset1:48
	ds_read2_b32 v[156:157], v140 offset0:32 offset1:48
	ds_read2_b32 v[158:159], v142 offset0:32 offset1:48
	ds_read2_b32 v[144:145], v134 offset0:128 offset1:144
	ds_read2_b32 v[146:147], v138 offset0:128 offset1:144
	ds_read2_b32 v[148:149], v140 offset0:128 offset1:144
	ds_read2_b32 v[150:151], v142 offset0:128 offset1:144
	s_waitcnt lgkmcnt(10)
	v_max_f32_e32 v130, v166, v166
	s_waitcnt lgkmcnt(9)
	v_max_f32_e32 v131, v164, v164
	v_max_f32_e32 v130, v131, v130
	s_waitcnt lgkmcnt(8)
	v_max3_f32 v135, v160, v162, v130
	v_sub_f32_e32 v124, v124, v135
	v_mul_f32_e32 v124, 0x3d800000, v124
	v_sub_f32_e32 v125, v125, v135
	v_mul_f32_e32 v124, 0x3fb8aa3b, v124
	v_mul_f32_e32 v125, 0x3d800000, v125
	v_sub_f32_e32 v126, v126, v135
	v_exp_f32_e32 v124, v124
	v_mul_f32_e32 v125, 0x3fb8aa3b, v125
	v_mul_f32_e32 v126, 0x3d800000, v126
	v_sub_f32_e32 v127, v127, v135
	v_exp_f32_e32 v125, v125
	v_mul_f32_e32 v126, 0x3fb8aa3b, v126
	v_mul_f32_e32 v127, 0x3d800000, v127
	v_exp_f32_e32 v126, v126
	v_mul_f32_e32 v127, 0x3fb8aa3b, v127
	v_exp_f32_e32 v127, v127
	v_add_f32_e32 v130, 0, v124
	v_sub_f32_e32 v116, v116, v135
	v_sub_f32_e32 v118, v118, v135
	v_add_f32_e32 v130, v125, v130
	v_mul_f32_e32 v116, 0x3d800000, v116
	v_sub_f32_e32 v117, v117, v135
	v_mul_f32_e32 v118, 0x3d800000, v118
	v_add_f32_e32 v130, v126, v130
	v_mul_f32_e32 v116, 0x3fb8aa3b, v116
	v_mul_f32_e32 v117, 0x3d800000, v117
	v_mul_f32_e32 v118, 0x3fb8aa3b, v118
	v_add_f32_e32 v139, v127, v130
	v_exp_f32_e32 v116, v116
	v_mul_f32_e32 v117, 0x3fb8aa3b, v117
	v_exp_f32_e32 v130, v118
	v_sub_f32_e32 v118, v119, v135
	v_exp_f32_e32 v117, v117
	v_mul_f32_e32 v118, 0x3d800000, v118
	v_mul_f32_e32 v118, 0x3fb8aa3b, v118
	v_exp_f32_e32 v131, v118
	v_add_f32_e32 v118, v116, v139
	v_add_f32_e32 v118, v117, v118
	v_add_f32_e32 v118, v130, v118
	v_add_f32_e32 v139, v131, v118
	v_sub_f32_e32 v118, v120, v135
	v_mul_f32_e32 v118, 0x3d800000, v118
	v_sub_f32_e32 v119, v121, v135
	v_mul_f32_e32 v118, 0x3fb8aa3b, v118
	v_mul_f32_e32 v119, 0x3d800000, v119
	v_sub_f32_e32 v120, v122, v135
	v_exp_f32_e32 v118, v118
	v_mul_f32_e32 v119, 0x3fb8aa3b, v119
	v_mul_f32_e32 v120, 0x3d800000, v120
	v_sub_f32_e32 v121, v123, v135
	v_exp_f32_e32 v119, v119
	v_mul_f32_e32 v120, 0x3fb8aa3b, v120
	v_mul_f32_e32 v121, 0x3d800000, v121
	v_sub_f32_e32 v112, v112, v135
	v_exp_f32_e32 v120, v120
	v_mul_f32_e32 v121, 0x3fb8aa3b, v121
	v_mul_f32_e32 v112, 0x3d800000, v112
	v_sub_f32_e32 v113, v113, v135
	v_exp_f32_e32 v121, v121
	v_mul_f32_e32 v112, 0x3fb8aa3b, v112
	v_mul_f32_e32 v113, 0x3d800000, v113
	v_sub_f32_e32 v114, v114, v135
	v_add_f32_e32 v122, v118, v139
	v_exp_f32_e32 v112, v112
	v_mul_f32_e32 v113, 0x3fb8aa3b, v113
	v_mul_f32_e32 v114, 0x3d800000, v114
	v_sub_f32_e32 v115, v115, v135
	v_add_f32_e32 v122, v119, v122
	v_exp_f32_e32 v113, v113
	v_mul_f32_e32 v114, 0x3fb8aa3b, v114
	v_mul_f32_e32 v115, 0x3d800000, v115
	v_add_f32_e32 v122, v120, v122
	v_exp_f32_e32 v114, v114
	v_mul_f32_e32 v115, 0x3fb8aa3b, v115
	v_add_f32_e32 v122, v121, v122
	v_exp_f32_e32 v115, v115
	v_add_f32_e32 v122, v112, v122
	v_add_f32_e32 v122, v113, v122
	v_add_f32_e32 v122, v114, v122
	v_add_f32_e32 v122, v115, v122
	ds_bpermute_b32 v123, v171, v122
	ds_read2_b32 v[134:135], v134 offset0:160 offset1:176
	ds_read2_b32 v[138:139], v138 offset0:160 offset1:176
	ds_read2_b32 v[140:141], v140 offset0:160 offset1:176
	ds_read2_b32 v[142:143], v142 offset0:160 offset1:176
	s_waitcnt lgkmcnt(0)
	s_barrier
	v_add_f32_e32 v122, v122, v123
	ds_bpermute_b32 v123, v172, v122
	s_and_saveexec_b64 s[34:35], vcc
	s_cbranch_execz .LBB0_1089
	s_waitcnt lgkmcnt(0)
	v_add_f32_e32 v122, v122, v123
	ds_write_b32 v173, v122

.LBB0_1103:
	s_or_b64 exec, exec, s[34:35]
	v_ashrrev_i32_e32 v74, 2, v169
	s_movk_i32 s29, 0xffc0
	v_and_or_b32 v134, v74, s29, v170
	v_lshl_add_u32 v142, v134, 2, s99
	s_waitcnt lgkmcnt(0)
	s_barrier
	v_bfe_u32 v185, v136, 7, 1
	v_lshlrev_b32_e32 v248, 15, v185
	v_lshrrev_b32_e32 v185, 8, v136
	v_lshl_or_b32 v248, v185, 13, v248
	v_bfe_u32 v185, v136, 6, 1
	v_lshl_or_b32 v248, v185, 10, v248
	v_and_b32_e32 v185, 15, v136
	v_lshl_or_b32 v248, v185, 6, v248
	v_bfe_u32 v185, v136, 4, 2
	v_lshl_or_b32 v248, v185, 3, v248
	v_bfe_u32 v185, v136, 3, 1
	v_lshl_or_b32 v248, v185, 5, v248
	v_xor_b32_e32 v249, 32, v248
	v_add_u32_e32 v250, 0x1a000, v248
	v_xor_b32_e32 v251, 32, v250
	v_readfirstlane_b32 s100, v136
	s_lshr_b32 s100, s100, 6
	ds_read2st64_b32 v[74:75], v142 offset1:4
	ds_read2st64_b32 v[138:139], v142 offset0:8 offset1:12
	v_lshlrev_b32_e32 v128, 6, v128
	v_lshl_add_u64 v[140:141], s[0:1], 0, v[128:129]
	v_lshlrev_b32_e32 v128, 3, v168
	s_waitcnt lgkmcnt(1)
	v_add_f32_e32 v74, v74, v75
	s_waitcnt lgkmcnt(0)
	v_add_f32_e32 v74, v74, v138
	v_add_f32_e32 v74, v74, v139
	v_div_scale_f32 v75, s[34:35], v74, v74, 1.0
	v_rcp_f32_e32 v143, v75
	v_lshl_add_u64 v[138:139], v[140:141], 0, v[128:129]
	v_ashrrev_i32_e32 v135, 31, v134
	v_fma_f32 v128, -v75, v143, 1.0
	v_fmac_f32_e32 v143, v128, v143
	v_div_scale_f32 v128, vcc, 1.0, v74, 1.0
	v_mul_f32_e32 v140, v128, v143
	v_fma_f32 v141, -v75, v140, v128
	v_fmac_f32_e32 v140, v141, v143
	v_fma_f32 v75, -v75, v140, v128
	v_div_fmas_f32 v75, v75, v143, v140
	v_div_fixup_f32 v128, v75, v74, 1.0
	v_lshlrev_b64 v[74:75], 9, v[134:135]
	v_pk_mul_f32 v[124:125], v[124:125], v[128:129] op_sel_hi:[1,0]
	v_lshl_add_u64 v[74:75], v[138:139], 0, v[74:75]
	v_pk_mul_f32 v[126:127], v[126:127], v[128:129] op_sel_hi:[1,0]
	v_cvt_pk_bf16_f32 v124, v124, v125
	v_pk_mul_f32 v[116:117], v[116:117], v[128:129] op_sel_hi:[1,0]
	v_cvt_pk_bf16_f32 v125, v126, v127
	ds_write_b64 v248, v[124:125]
	v_pk_mul_f32 v[124:125], v[130:131], v[128:129] op_sel_hi:[1,0]
	v_cvt_pk_bf16_f32 v116, v116, v117
	v_pk_mul_f32 v[118:119], v[118:119], v[128:129] op_sel_hi:[1,0]
	v_cvt_pk_bf16_f32 v117, v124, v125
	v_pk_mul_f32 v[112:113], v[112:113], v[128:129] op_sel_hi:[1,0]
	ds_write_b64 v249, v[116:117]
	v_pk_mul_f32 v[116:117], v[120:121], v[128:129] op_sel_hi:[1,0]
	v_cvt_pk_bf16_f32 v224, v118, v119
	v_pk_mul_f32 v[114:115], v[114:115], v[128:129] op_sel_hi:[1,0]
	v_cvt_pk_bf16_f32 v225, v116, v117
	v_cvt_pk_bf16_f32 v226, v112, v113
	v_cvt_pk_bf16_f32 v227, v114, v115
	v_add_u32_e32 v118, 64, v142
	ds_read2st64_b32 v[112:113], v118 offset1:4
	ds_read2st64_b32 v[114:115], v118 offset0:8 offset1:12
	v_or_b32_e32 v116, 16, v134
	v_ashrrev_i32_e32 v117, 31, v116
	s_waitcnt lgkmcnt(1)
	v_add_f32_e32 v112, v112, v113
	s_waitcnt lgkmcnt(0)
	v_add_f32_e32 v112, v112, v114
	v_add_f32_e32 v112, v112, v115
	v_div_scale_f32 v113, s[34:35], v112, v112, 1.0
	v_rcp_f32_e32 v114, v113
	v_div_scale_f32 v115, vcc, 1.0, v112, 1.0
	v_fma_f32 v119, -v113, v114, 1.0
	v_fmac_f32_e32 v114, v119, v114
	v_mul_f32_e32 v119, v115, v114
	v_fma_f32 v120, -v113, v119, v115
	v_fmac_f32_e32 v119, v120, v114
	v_fma_f32 v113, -v113, v119, v115
	v_div_fmas_f32 v113, v113, v114, v119
	v_div_fixup_f32 v112, v113, v112, 1.0
	v_lshlrev_b64 v[114:115], 9, v[116:117]
	v_pk_mul_f32 v[108:109], v[108:109], v[112:113] op_sel_hi:[1,0]
	v_lshl_add_u64 v[114:115], v[138:139], 0, v[114:115]
	v_pk_mul_f32 v[110:111], v[110:111], v[112:113] op_sel_hi:[1,0]
	v_cvt_pk_bf16_f32 v108, v108, v109
	v_pk_mul_f32 v[100:101], v[100:101], v[112:113] op_sel_hi:[1,0]
	v_cvt_pk_bf16_f32 v109, v110, v111
	ds_write_b64 v248, v[108:109] offset:2048
	v_pk_mul_f32 v[108:109], v[122:123], v[112:113] op_sel_hi:[1,0]
	v_cvt_pk_bf16_f32 v100, v100, v101
	v_pk_mul_f32 v[102:103], v[102:103], v[112:113] op_sel_hi:[1,0]
	v_cvt_pk_bf16_f32 v101, v108, v109
	v_pk_mul_f32 v[96:97], v[96:97], v[112:113] op_sel_hi:[1,0]
	ds_write_b64 v249, v[100:101] offset:2048
	v_pk_mul_f32 v[100:101], v[104:105], v[112:113] op_sel_hi:[1,0]
	v_cvt_pk_bf16_f32 v228, v102, v103
	v_pk_mul_f32 v[98:99], v[98:99], v[112:113] op_sel_hi:[1,0]
	v_cvt_pk_bf16_f32 v229, v100, v101
	v_cvt_pk_bf16_f32 v230, v96, v97
	v_cvt_pk_bf16_f32 v231, v98, v99
	v_add_u32_e32 v102, 0x80, v142
	ds_read2st64_b32 v[96:97], v102 offset1:4
	ds_read2st64_b32 v[98:99], v102 offset0:8 offset1:12
	v_or_b32_e32 v100, 32, v134
	v_ashrrev_i32_e32 v101, 31, v100
	s_waitcnt lgkmcnt(1)
	v_add_f32_e32 v96, v96, v97
	s_waitcnt lgkmcnt(0)
	v_add_f32_e32 v96, v96, v98
	v_add_f32_e32 v96, v96, v99
	v_div_scale_f32 v97, s[34:35], v96, v96, 1.0
	v_rcp_f32_e32 v98, v97
	v_div_scale_f32 v99, vcc, 1.0, v96, 1.0
	v_fma_f32 v103, -v97, v98, 1.0
	v_fmac_f32_e32 v98, v103, v98
	v_mul_f32_e32 v103, v99, v98
	v_fma_f32 v104, -v97, v103, v99
	v_fmac_f32_e32 v103, v104, v98
	v_fma_f32 v97, -v97, v103, v99
	v_div_fmas_f32 v97, v97, v98, v103
	v_div_fixup_f32 v96, v97, v96, 1.0
	v_lshlrev_b64 v[98:99], 9, v[100:101]
	v_pk_mul_f32 v[92:93], v[92:93], v[96:97] op_sel_hi:[1,0]
	v_lshl_add_u64 v[98:99], v[138:139], 0, v[98:99]
	v_pk_mul_f32 v[94:95], v[94:95], v[96:97] op_sel_hi:[1,0]
	v_cvt_pk_bf16_f32 v92, v92, v93
	v_pk_mul_f32 v[84:85], v[84:85], v[96:97] op_sel_hi:[1,0]
	v_cvt_pk_bf16_f32 v93, v94, v95
	ds_write_b64 v248, v[92:93] offset:4096
	v_pk_mul_f32 v[92:93], v[106:107], v[96:97] op_sel_hi:[1,0]
	v_cvt_pk_bf16_f32 v84, v84, v85
	v_pk_mul_f32 v[86:87], v[86:87], v[96:97] op_sel_hi:[1,0]
	v_cvt_pk_bf16_f32 v85, v92, v93
	v_pk_mul_f32 v[80:81], v[80:81], v[96:97] op_sel_hi:[1,0]
	ds_write_b64 v249, v[84:85] offset:4096
	v_pk_mul_f32 v[84:85], v[88:89], v[96:97] op_sel_hi:[1,0]
	v_cvt_pk_bf16_f32 v232, v86, v87
	v_pk_mul_f32 v[82:83], v[82:83], v[96:97] op_sel_hi:[1,0]
	v_cvt_pk_bf16_f32 v233, v84, v85
	v_cvt_pk_bf16_f32 v234, v80, v81
	v_cvt_pk_bf16_f32 v235, v82, v83
	v_add_u32_e32 v86, 0xc0, v142
	ds_read2st64_b32 v[80:81], v86 offset1:4
	ds_read2st64_b32 v[82:83], v86 offset0:8 offset1:12
	v_or_b32_e32 v84, 48, v134
	v_ashrrev_i32_e32 v85, 31, v84
	s_waitcnt lgkmcnt(1)
	v_add_f32_e32 v80, v80, v81
	s_waitcnt lgkmcnt(0)
	v_add_f32_e32 v80, v80, v82
	v_add_f32_e32 v80, v80, v83
	v_div_scale_f32 v81, s[34:35], v80, v80, 1.0
	v_rcp_f32_e32 v82, v81
	v_div_scale_f32 v83, vcc, 1.0, v80, 1.0
	v_fma_f32 v87, -v81, v82, 1.0
	v_fmac_f32_e32 v82, v87, v82
	v_mul_f32_e32 v87, v83, v82
	v_fma_f32 v88, -v81, v87, v83
	v_fmac_f32_e32 v87, v88, v82
	v_fma_f32 v81, -v81, v87, v83
	v_div_fmas_f32 v81, v81, v82, v87
	v_div_fixup_f32 v80, v81, v80, 1.0
	v_lshlrev_b64 v[82:83], 9, v[84:85]
	v_pk_mul_f32 v[76:77], v[76:77], v[80:81] op_sel_hi:[1,0]
	v_lshl_add_u64 v[82:83], v[138:139], 0, v[82:83]
	v_pk_mul_f32 v[78:79], v[78:79], v[80:81] op_sel_hi:[1,0]
	v_cvt_pk_bf16_f32 v76, v76, v77
	v_pk_mul_f32 v[68:69], v[68:69], v[80:81] op_sel_hi:[1,0]
	v_cvt_pk_bf16_f32 v77, v78, v79
	ds_write_b64 v248, v[76:77] offset:6144
	v_pk_mul_f32 v[76:77], v[90:91], v[80:81] op_sel_hi:[1,0]
	v_cvt_pk_bf16_f32 v68, v68, v69
	v_pk_mul_f32 v[70:71], v[70:71], v[80:81] op_sel_hi:[1,0]
	v_cvt_pk_bf16_f32 v69, v76, v77
	v_pk_mul_f32 v[64:65], v[64:65], v[80:81] op_sel_hi:[1,0]
	ds_write_b64 v249, v[68:69] offset:6144
	v_pk_mul_f32 v[68:69], v[72:73], v[80:81] op_sel_hi:[1,0]
	v_cvt_pk_bf16_f32 v236, v70, v71
	v_pk_mul_f32 v[66:67], v[66:67], v[80:81] op_sel_hi:[1,0]
	v_cvt_pk_bf16_f32 v237, v68, v69
	v_cvt_pk_bf16_f32 v238, v64, v65
	v_cvt_pk_bf16_f32 v239, v66, v67
	ds_read2st64_b32 v[64:65], v142 offset0:2 offset1:6
	ds_read2st64_b32 v[66:67], v142 offset0:10 offset1:14
	s_mov_b32 s29, 0x10000
	s_mov_b64 s[34:35], 0x10000
	s_waitcnt lgkmcnt(1)
	v_add_f32_e32 v64, v64, v65
	s_waitcnt lgkmcnt(0)
	v_add_f32_e32 v64, v64, v66
	v_add_f32_e32 v66, v64, v67
	v_div_scale_f32 v67, s[40:41], v66, v66, 1.0
	v_rcp_f32_e32 v68, v67
	v_div_scale_f32 v69, vcc, 1.0, v66, 1.0
	v_lshl_add_u64 v[64:65], v[74:75], 0, s[34:35]
	v_fma_f32 v70, -v67, v68, 1.0
	v_fmac_f32_e32 v68, v70, v68
	v_mul_f32_e32 v70, v69, v68
	v_fma_f32 v71, -v67, v70, v69
	v_fmac_f32_e32 v70, v71, v68
	v_fma_f32 v67, -v67, v70, v69
	v_div_fmas_f32 v67, v67, v68, v70
	v_div_fixup_f32 v66, v67, v66, 1.0
	v_pk_mul_f32 v[62:63], v[62:63], v[66:67] op_sel_hi:[1,0]
	v_pk_mul_f32 v[60:61], v[60:61], v[66:67] op_sel_hi:[1,0]
	v_pk_mul_f32 v[56:57], v[56:57], v[66:67] op_sel_hi:[1,0]
	v_cvt_pk_bf16_f32 v60, v60, v61
	v_cvt_pk_bf16_f32 v61, v62, v63
	v_add_co_u32_e32 v62, vcc, s29, v74
	v_pk_mul_f32 v[52:53], v[52:53], v[66:67] op_sel_hi:[1,0]
	s_nop 0
	v_addc_co_u32_e32 v63, vcc, 0, v75, vcc
	v_pk_mul_f32 v[48:49], v[48:49], v[66:67] op_sel_hi:[1,0]
	ds_write_b64 v248, v[60:61] offset:16384
	v_pk_mul_f32 v[58:59], v[58:59], v[66:67] op_sel_hi:[1,0]
	v_cvt_pk_bf16_f32 v56, v56, v57
	v_pk_mul_f32 v[54:55], v[54:55], v[66:67] op_sel_hi:[1,0]
	v_cvt_pk_bf16_f32 v57, v58, v59
	ds_write_b64 v249, v[56:57] offset:16384
	v_cvt_pk_bf16_f32 v208, v52, v53
	v_cvt_pk_bf16_f32 v209, v54, v55
	v_pk_mul_f32 v[50:51], v[50:51], v[66:67] op_sel_hi:[1,0]
	v_cvt_pk_bf16_f32 v210, v48, v49
	s_nop 0
	v_cvt_pk_bf16_f32 v211, v50, v51
	ds_read2st64_b32 v[48:49], v118 offset0:2 offset1:6
	ds_read2st64_b32 v[50:51], v118 offset0:10 offset1:14
	s_mov_b32 s29, 0x12000
	s_waitcnt lgkmcnt(1)
	v_add_f32_e32 v48, v48, v49
	s_waitcnt lgkmcnt(0)
	v_add_f32_e32 v48, v48, v50
	v_add_f32_e32 v50, v48, v51
	v_div_scale_f32 v51, s[34:35], v50, v50, 1.0
	v_rcp_f32_e32 v52, v51
	v_div_scale_f32 v53, vcc, 1.0, v50, 1.0
	v_lshl_add_u64 v[48:49], v[74:75], 0, s[22:23]
	v_fma_f32 v54, -v51, v52, 1.0
	v_fmac_f32_e32 v52, v54, v52
	v_mul_f32_e32 v54, v53, v52
	v_fma_f32 v55, -v51, v54, v53
	v_fmac_f32_e32 v54, v55, v52
	v_fma_f32 v51, -v51, v54, v53
	v_div_fmas_f32 v51, v51, v52, v54
	v_div_fixup_f32 v50, v51, v50, 1.0
	v_pk_mul_f32 v[46:47], v[46:47], v[50:51] op_sel_hi:[1,0]
	v_pk_mul_f32 v[44:45], v[44:45], v[50:51] op_sel_hi:[1,0]
	v_pk_mul_f32 v[40:41], v[40:41], v[50:51] op_sel_hi:[1,0]
	v_cvt_pk_bf16_f32 v44, v44, v45
	v_cvt_pk_bf16_f32 v45, v46, v47
	v_add_co_u32_e32 v46, vcc, s29, v74
	v_pk_mul_f32 v[36:37], v[36:37], v[50:51] op_sel_hi:[1,0]
	s_nop 0
	v_addc_co_u32_e32 v47, vcc, 0, v75, vcc
	v_pk_mul_f32 v[32:33], v[32:33], v[50:51] op_sel_hi:[1,0]
	ds_write_b64 v248, v[44:45] offset:18432
	v_pk_mul_f32 v[42:43], v[42:43], v[50:51] op_sel_hi:[1,0]
	v_cvt_pk_bf16_f32 v40, v40, v41
	v_pk_mul_f32 v[38:39], v[38:39], v[50:51] op_sel_hi:[1,0]
	v_cvt_pk_bf16_f32 v41, v42, v43
	ds_write_b64 v249, v[40:41] offset:18432
	v_cvt_pk_bf16_f32 v212, v36, v37
	v_cvt_pk_bf16_f32 v213, v38, v39
	v_pk_mul_f32 v[34:35], v[34:35], v[50:51] op_sel_hi:[1,0]
	v_cvt_pk_bf16_f32 v214, v32, v33
	s_nop 0
	v_cvt_pk_bf16_f32 v215, v34, v35
	ds_read2st64_b32 v[32:33], v102 offset0:2 offset1:6
	ds_read2st64_b32 v[34:35], v102 offset0:10 offset1:14
	s_mov_b32 s29, 0x14000
	s_waitcnt lgkmcnt(1)
	v_add_f32_e32 v32, v32, v33
	s_waitcnt lgkmcnt(0)
	v_add_f32_e32 v32, v32, v34
	v_add_f32_e32 v34, v32, v35
	v_div_scale_f32 v35, s[34:35], v34, v34, 1.0
	v_rcp_f32_e32 v36, v35
	v_div_scale_f32 v37, vcc, 1.0, v34, 1.0
	v_lshl_add_u64 v[32:33], v[74:75], 0, s[24:25]
	v_fma_f32 v38, -v35, v36, 1.0
	v_fmac_f32_e32 v36, v38, v36
	v_mul_f32_e32 v38, v37, v36
	v_fma_f32 v39, -v35, v38, v37
	v_fmac_f32_e32 v38, v39, v36
	v_fma_f32 v35, -v35, v38, v37
	v_div_fmas_f32 v35, v35, v36, v38
	v_div_fixup_f32 v34, v35, v34, 1.0
	v_pk_mul_f32 v[30:31], v[30:31], v[34:35] op_sel_hi:[1,0]
	v_pk_mul_f32 v[28:29], v[28:29], v[34:35] op_sel_hi:[1,0]
	v_pk_mul_f32 v[24:25], v[24:25], v[34:35] op_sel_hi:[1,0]
	v_cvt_pk_bf16_f32 v28, v28, v29
	v_cvt_pk_bf16_f32 v29, v30, v31
	v_add_co_u32_e32 v30, vcc, s29, v74
	v_pk_mul_f32 v[20:21], v[20:21], v[34:35] op_sel_hi:[1,0]
	s_nop 0
	v_addc_co_u32_e32 v31, vcc, 0, v75, vcc
	v_pk_mul_f32 v[16:17], v[16:17], v[34:35] op_sel_hi:[1,0]
	ds_write_b64 v248, v[28:29] offset:20480
	v_pk_mul_f32 v[26:27], v[26:27], v[34:35] op_sel_hi:[1,0]
	v_cvt_pk_bf16_f32 v24, v24, v25
	v_pk_mul_f32 v[22:23], v[22:23], v[34:35] op_sel_hi:[1,0]
	v_cvt_pk_bf16_f32 v25, v26, v27
	ds_write_b64 v249, v[24:25] offset:20480
	v_cvt_pk_bf16_f32 v216, v20, v21
	v_cvt_pk_bf16_f32 v217, v22, v23
	v_pk_mul_f32 v[18:19], v[18:19], v[34:35] op_sel_hi:[1,0]
	v_cvt_pk_bf16_f32 v218, v16, v17
	s_nop 0
	v_cvt_pk_bf16_f32 v219, v18, v19
	ds_read2st64_b32 v[16:17], v86 offset0:2 offset1:6
	ds_read2st64_b32 v[18:19], v86 offset0:10 offset1:14
	s_mov_b32 s29, 0x16000
	s_waitcnt lgkmcnt(1)
	v_add_f32_e32 v16, v16, v17
	s_waitcnt lgkmcnt(0)
	v_add_f32_e32 v16, v16, v18
	v_add_f32_e32 v18, v16, v19
	v_div_scale_f32 v19, s[34:35], v18, v18, 1.0
	v_rcp_f32_e32 v20, v19
	v_div_scale_f32 v21, vcc, 1.0, v18, 1.0
	v_lshl_add_u64 v[16:17], v[74:75], 0, s[26:27]
	v_fma_f32 v22, -v19, v20, 1.0
	v_fmac_f32_e32 v20, v22, v20
	v_mul_f32_e32 v22, v21, v20
	v_fma_f32 v23, -v19, v22, v21
	v_fmac_f32_e32 v22, v23, v20
	v_fma_f32 v19, -v19, v22, v21
	v_div_fmas_f32 v19, v19, v20, v22
	v_div_fixup_f32 v18, v19, v18, 1.0
	v_pk_mul_f32 v[14:15], v[14:15], v[18:19] op_sel_hi:[1,0]
	v_pk_mul_f32 v[12:13], v[12:13], v[18:19] op_sel_hi:[1,0]
	v_pk_mul_f32 v[10:11], v[10:11], v[18:19] op_sel_hi:[1,0]
	v_cvt_pk_bf16_f32 v12, v12, v13
	v_cvt_pk_bf16_f32 v13, v14, v15
	v_add_co_u32_e32 v14, vcc, s29, v74
	v_pk_mul_f32 v[8:9], v[8:9], v[18:19] op_sel_hi:[1,0]
	s_nop 0
	v_addc_co_u32_e32 v15, vcc, 0, v75, vcc
	v_pk_mul_f32 v[6:7], v[6:7], v[18:19] op_sel_hi:[1,0]
	v_pk_mul_f32 v[4:5], v[4:5], v[18:19] op_sel_hi:[1,0]
	v_pk_mul_f32 v[0:1], v[0:1], v[18:19] op_sel_hi:[1,0]
	ds_write_b64 v248, v[12:13] offset:22528
	v_cvt_pk_bf16_f32 v8, v8, v9
	v_cvt_pk_bf16_f32 v9, v10, v11
	ds_write_b64 v249, v[8:9] offset:22528
	v_cvt_pk_bf16_f32 v220, v4, v5
	v_cvt_pk_bf16_f32 v221, v6, v7
	v_pk_mul_f32 v[2:3], v[2:3], v[18:19] op_sel_hi:[1,0]
	v_cvt_pk_bf16_f32 v222, v0, v1
	s_nop 0
	v_cvt_pk_bf16_f32 v223, v2, v3
	v_mov_b32_e32 v10, v136
	s_waitcnt vmcnt(0)
	s_bitcmp1_b32 s100, 1
	s_cbranch_scc0 .Lpv2_x
	ds_write_b64 v250, v[208:209]
	ds_write_b64 v251, v[210:211]
	ds_write_b64 v250, v[212:213] offset:2048
	ds_write_b64 v251, v[214:215] offset:2048
	ds_write_b64 v250, v[216:217] offset:4096
	ds_write_b64 v251, v[218:219] offset:4096
	ds_write_b64 v250, v[220:221] offset:6144
	ds_write_b64 v251, v[222:223] offset:6144
.Lpv2_x:
	s_waitcnt lgkmcnt(0)
	s_barrier
	s_lshl_b64 s[30:31], s[30:31], 1
	v_bfe_i32 v2, v10, 27, 1
	v_lshlrev_b32_e32 v0, 4, v10
	v_lshrrev_b32_e32 v2, 22, v2
	v_add_u32_e32 v2, v0, v2
	v_and_b32_e32 v2, 0xfffffc00, v2
	v_sub_u32_e32 v2, v0, v2
	v_lshrrev_b32_e32 v3, 4, v2
	v_bitop3_b32 v2, v3, v2, 32 bitop3:0x6c
	v_ashrrev_i32_e32 v1, 31, v10
	v_ashrrev_i32_e32 v4, 31, v2
	v_lshrrev_b32_e32 v1, 26, v1
	v_lshrrev_b32_e32 v4, 26, v4
	v_add_u32_e32 v1, v10, v1
	v_add_u32_e32 v4, v2, v4
	v_ashrrev_i32_e32 v1, 6, v1
	v_lshrrev_b32_e32 v5, 6, v4
	v_and_b32_e32 v4, 0xc0, v4
	v_lshlrev_b32_e32 v3, 3, v1
	v_lshlrev_b32_e32 v1, 5, v1
	v_sub_u32_e32 v2, v2, v4
	v_and_b32_e32 v3, 0x7ffff0, v3
	v_and_b32_e32 v1, 32, v1
	v_ashrrev_i16_sdwa v2, v133, sext(v2) dst_sel:DWORD dst_unused:UNUSED_PAD src0_sel:DWORD src1_sel:BYTE_0
	v_add_u32_sdwa v1, v1, sext(v2) dst_sel:DWORD dst_unused:UNUSED_PAD src0_sel:DWORD src1_sel:WORD_0
	v_add_lshl_u32 v2, v5, v3, 9
	v_add_u32_e32 v0, 0x2000, v0
	v_lshl_add_u32 v128, v1, 1, v2
	v_ashrrev_i32_e32 v1, 31, v0
	v_lshrrev_b32_e32 v1, 22, v1
	v_add_u32_e32 v1, v0, v1
	v_ashrrev_i32_e32 v1, 10, v1
	v_mul_i32_i24_e32 v2, 0x400, v1
	v_sub_u32_e32 v0, v0, v2
	v_lshrrev_b32_e32 v2, 4, v0
	v_bitop3_b32 v0, v2, v0, 32 bitop3:0x6c
	v_ashrrev_i32_e32 v3, 31, v0
	v_lshrrev_b32_e32 v3, 26, v3
	s_add_u32 s30, s66, s30
	v_readfirstlane_b32 s29, v10
	v_add_u32_e32 v3, v0, v3
	s_addc_u32 s31, s67, s31
	v_lshrrev_b32_e32 v4, 6, v3
	v_and_b32_e32 v3, 0xc0, v3
	s_ashr_i32 s34, s29, 6
	v_lshlrev_b32_e32 v2, 3, v1
	v_lshlrev_b32_e32 v1, 5, v1
	v_sub_u32_e32 v0, v0, v3
	s_lshl_b32 s53, s34, 10
	v_and_b32_e32 v2, 0x7ffff0, v2
	v_and_b32_e32 v1, 32, v1
	v_ashrrev_i16_sdwa v0, v133, sext(v0) dst_sel:DWORD dst_unused:UNUSED_PAD src0_sel:DWORD src1_sel:BYTE_0
	s_add_i32 s73, s53, 0
	v_add_u32_sdwa v0, v1, sext(v0) dst_sel:DWORD dst_unused:UNUSED_PAD src0_sel:DWORD src1_sel:WORD_0
	v_add_lshl_u32 v1, v4, v2, 9
	s_add_i32 m0, s73, 0x10000
	v_lshl_add_u32 v0, v0, 1, v1
	global_load_lds_dwordx4 v128, s[30:31]
	s_add_i32 m0, s73, 0x12000
	s_ashr_i32 s33, s29, 8
	global_load_lds_dwordx4 v0, s[30:31]
	s_mov_b32 m0, s73
	s_add_i32 s74, s73, 0x2000
	s_mov_b32 m0, s74
	s_add_u32 s40, s30, 0x10000
	s_addc_u32 s41, s31, 0
	s_add_i32 m0, s73, 0x14000
	s_add_i32 s35, s73, 0x6000
	global_load_lds_dwordx4 v128, s[40:41]
	s_add_i32 m0, s73, 0x16000
	v_mov_b32_e32 v1, v129
	global_load_lds_dwordx4 v0, s[40:41]
	s_add_i32 s41, s73, 0x4000
	s_mov_b32 m0, s41
	v_lshl_add_u64 v[6:7], s[30:31], 0, v[128:129]
	s_mov_b32 m0, s35
	s_cmp_lg_u32 s33, 1
	v_lshl_add_u64 v[8:9], s[30:31], 0, v[0:1]
	s_cbranch_scc1 .LBB0_1105
	s_barrier
.LBB0_1105:
	v_and_b32_e32 v11, 15, v10
	v_and_b32_e32 v12, 48, v10
	v_lshlrev_b32_e32 v10, 2, v10
	v_lshlrev_b32_e32 v11, 6, v11
	v_and_b32_e32 v10, 32, v10
	s_lshl_b32 s34, s34, 12
	v_or_b32_e32 v13, v11, v12
	v_bitop3_b32 v11, v11, v10, v12 bitop3:0x36
	s_lshl_b32 s33, s33, 13
	s_and_b32 s34, s34, 0x3000
	s_add_i32 s68, s46, s53
	v_or_b32_e32 v12, s34, v11
	v_bitop3_b32 v13, v13, s33, v10 bitop3:0xde
	v_lshl_add_u64 v[10:11], v[6:7], 0, s[16:17]
	s_mov_b32 m0, s68
	s_add_i32 s57, s68, 0x2000
	v_lshl_add_u64 v[4:5], s[0:1], 0, v[128:129]
	s_waitcnt vmcnt(2)
	s_barrier
	global_load_lds_dwordx4 v[10:11], off
	v_lshl_add_u64 v[10:11], v[8:9], 0, s[16:17]
	s_mov_b32 m0, s57
	s_add_i32 s56, s73, 0x8000
	s_add_i32 s40, s73, 0xa000
	v_lshl_add_u64 v[2:3], s[0:1], 0, v[0:1]
	global_load_lds_dwordx4 v[10:11], off
	v_lshl_add_u64 v[10:11], v[4:5], 0, s[16:17]
	s_mov_b32 m0, s56
	s_add_u32 s76, s30, 0x10080
	v_lshl_add_u64 v[10:11], v[2:3], 0, s[16:17]
	s_mov_b32 m0, s40
	s_addc_u32 s77, s31, 0
	s_add_i32 s34, s47, s53
	v_lshl_add_u64 v[10:11], s[76:77], 0, v[128:129]
	s_mov_b32 m0, s34
	s_add_i32 s33, s34, 0x2000
	global_load_lds_dwordx4 v[10:11], off
	v_lshl_add_u64 v[10:11], s[76:77], 0, v[0:1]
	s_mov_b32 m0, s33
	v_add_u32_e32 v134, s43, v12
	global_load_lds_dwordx4 v[10:11], off
	v_add_u32_e32 v11, s42, v12
	s_waitcnt vmcnt(4)
	s_barrier
	v_add_u32_e32 v10, 0, v13
	v_add_u32_e32 v135, s46, v12
	v_add_u32_e32 v184, s47, v12
	ds_read_b128 v[12:15], v11
	ds_read_b128 v[16:19], v11 offset:1024
	ds_read_b128 v[20:23], v11 offset:2048
	ds_read_b128 v[24:27], v11 offset:3072
	s_add_i32 s72, s73, 0xc000
	v_lshl_add_u64 v[60:61], s[10:11], 0, v[128:129]
	s_mov_b32 m0, s72
	s_add_i32 s69, s73, 0xe000
	ds_read_b128 v[28:31], v10
	ds_read_b128 v[32:35], v10 offset:1024
	ds_read_b128 v[36:39], v10 offset:2048
	ds_read_b128 v[40:43], v10 offset:3072
	ds_read_b128 v[44:47], v10 offset:4096
	ds_read_b128 v[48:51], v10 offset:5120
	ds_read_b128 v[52:55], v10 offset:6144
	ds_read_b128 v[56:59], v10 offset:7168
	v_lshl_add_u64 v[60:61], s[10:11], 0, v[0:1]
	s_mov_b32 m0, s69
	s_nop 0
	s_waitcnt lgkmcnt(8)
	s_barrier
	s_waitcnt lgkmcnt(0)
	s_setprio 1
	s_waitcnt lgkmcnt(0)
	v_mfma_f32_16x16x32_bf16 v[60:63], v[12:15], v[28:31], 0
	v_mfma_f32_16x16x32_bf16 v[64:67], v[20:23], v[28:31], 0
	v_mfma_f32_16x16x32_bf16 v[68:71], v[12:15], v[36:39], 0
	v_mfma_f32_16x16x32_bf16 v[72:75], v[20:23], v[36:39], 0
	v_mfma_f32_16x16x32_bf16 v[76:79], v[12:15], v[44:47], 0
	v_mfma_f32_16x16x32_bf16 v[80:83], v[20:23], v[44:47], 0
	v_mfma_f32_16x16x32_bf16 v[84:87], v[12:15], v[52:55], 0
	v_mfma_f32_16x16x32_bf16 v[88:91], v[20:23], v[52:55], 0
	v_mfma_f32_16x16x32_bf16 v[60:63], v[16:19], v[32:35], v[60:63]
	v_mfma_f32_16x16x32_bf16 v[64:67], v[24:27], v[32:35], v[64:67]
	v_mfma_f32_16x16x32_bf16 v[68:71], v[16:19], v[40:43], v[68:71]
	v_mfma_f32_16x16x32_bf16 v[72:75], v[24:27], v[40:43], v[72:75]
	v_mfma_f32_16x16x32_bf16 v[76:79], v[16:19], v[48:51], v[76:79]
	v_mfma_f32_16x16x32_bf16 v[80:83], v[24:27], v[48:51], v[80:83]
	v_mfma_f32_16x16x32_bf16 v[84:87], v[16:19], v[56:59], v[84:87]
	v_mfma_f32_16x16x32_bf16 v[88:91], v[24:27], v[56:59], v[88:91]
	s_setprio 0
	s_barrier
	s_add_i32 s75, s42, s53
	v_lshl_add_u64 v[108:109], v[6:7], 0, s[18:19]
	s_mov_b32 m0, s75
	ds_read_b128 v[92:95], v134
	ds_read_b128 v[96:99], v134 offset:1024
	ds_read_b128 v[100:103], v134 offset:2048
	ds_read_b128 v[104:107], v134 offset:3072
	global_load_lds_dwordx4 v[108:109], off
	v_lshl_add_u64 v[108:109], v[8:9], 0, s[18:19]
	s_add_i32 m0, s75, 0x2000
	s_nop 0
	global_load_lds_dwordx4 v[108:109], off
	s_barrier
	s_waitcnt lgkmcnt(0)
	s_setprio 1
	s_waitcnt lgkmcnt(0)
	v_mfma_f32_16x16x32_bf16 v[108:111], v[92:95], v[28:31], 0
	v_mfma_f32_16x16x32_bf16 v[28:31], v[100:103], v[28:31], 0
	v_mfma_f32_16x16x32_bf16 v[108:111], v[96:99], v[32:35], v[108:111]
	v_mfma_f32_16x16x32_bf16 v[28:31], v[104:107], v[32:35], v[28:31]
	v_mfma_f32_16x16x32_bf16 v[32:35], v[92:95], v[36:39], 0
	v_mfma_f32_16x16x32_bf16 v[36:39], v[100:103], v[36:39], 0
	v_mfma_f32_16x16x32_bf16 v[32:35], v[96:99], v[40:43], v[32:35]
	v_mfma_f32_16x16x32_bf16 v[36:39], v[104:107], v[40:43], v[36:39]
	v_mfma_f32_16x16x32_bf16 v[40:43], v[92:95], v[44:47], 0
	v_mfma_f32_16x16x32_bf16 v[44:47], v[100:103], v[44:47], 0
	v_mfma_f32_16x16x32_bf16 v[40:43], v[96:99], v[48:51], v[40:43]
	v_mfma_f32_16x16x32_bf16 v[44:47], v[104:107], v[48:51], v[44:47]
	v_mfma_f32_16x16x32_bf16 v[48:51], v[92:95], v[52:55], 0
	v_mfma_f32_16x16x32_bf16 v[52:55], v[100:103], v[52:55], 0
	v_mfma_f32_16x16x32_bf16 v[48:51], v[96:99], v[56:59], v[48:51]
	v_mfma_f32_16x16x32_bf16 v[52:55], v[104:107], v[56:59], v[52:55]
	s_setprio 0
	s_mov_b32 m0, s73
	v_lshl_add_u64 v[130:131], v[4:5], 0, s[18:19]
	s_barrier
	ds_read_b128 v[56:59], v10 offset:16384
	ds_read_b128 v[112:115], v10 offset:17408
	ds_read_b128 v[116:119], v10 offset:18432
	ds_read_b128 v[120:123], v10 offset:19456
	ds_read_b128 v[124:127], v10 offset:20480
	ds_read_b128 v[138:141], v10 offset:21504
	ds_read_b128 v[142:145], v10 offset:22528
	ds_read_b128 v[146:149], v10 offset:23552
	s_bitcmp1_b32 s100, 1
	s_cbranch_scc1 .Lpv2_a
	ds_write_b64 v248, v[224:225]
	ds_write_b64 v249, v[226:227]
	ds_write_b64 v248, v[228:229] offset:2048
	ds_write_b64 v249, v[230:231] offset:2048
	ds_write_b64 v248, v[232:233] offset:4096
	ds_write_b64 v249, v[234:235] offset:4096
	ds_write_b64 v248, v[236:237] offset:6144
	ds_write_b64 v249, v[238:239] offset:6144
.Lpv2_a:
	v_lshl_add_u64 v[130:131], v[2:3], 0, s[18:19]
	s_mov_b32 m0, s74
	s_nop 0
	s_barrier
	s_waitcnt lgkmcnt(0)
	s_setprio 1
	s_waitcnt lgkmcnt(0)
	v_mfma_f32_16x16x32_bf16 v[150:153], v[12:15], v[56:59], 0
	v_mfma_f32_16x16x32_bf16 v[158:161], v[12:15], v[116:119], 0
	v_mfma_f32_16x16x32_bf16 v[166:169], v[12:15], v[124:127], 0
	v_mfma_f32_16x16x32_bf16 v[12:15], v[12:15], v[142:145], 0
	v_mfma_f32_16x16x32_bf16 v[150:153], v[16:19], v[112:115], v[150:153]
	v_mfma_f32_16x16x32_bf16 v[158:161], v[16:19], v[120:123], v[158:161]
	v_mfma_f32_16x16x32_bf16 v[166:169], v[16:19], v[138:141], v[166:169]
	v_mfma_f32_16x16x32_bf16 v[12:15], v[16:19], v[146:149], v[12:15]
	v_mfma_f32_16x16x32_bf16 v[16:19], v[20:23], v[142:145], 0
	v_mfma_f32_16x16x32_bf16 v[154:157], v[20:23], v[56:59], 0
	v_mfma_f32_16x16x32_bf16 v[162:165], v[20:23], v[116:119], 0
	v_mfma_f32_16x16x32_bf16 v[170:173], v[20:23], v[124:127], 0
	v_mfma_f32_16x16x32_bf16 v[16:19], v[24:27], v[146:149], v[16:19]
	v_mfma_f32_16x16x32_bf16 v[154:157], v[24:27], v[112:115], v[154:157]
	v_mfma_f32_16x16x32_bf16 v[162:165], v[24:27], v[120:123], v[162:165]
	v_mfma_f32_16x16x32_bf16 v[170:173], v[24:27], v[138:141], v[170:173]
	s_setprio 0
	s_barrier
	s_add_u32 s74, s30, 0x10100
	s_addc_u32 s75, s31, 0
	s_add_i32 s53, s43, s53
	v_lshl_add_u64 v[20:21], s[74:75], 0, v[128:129]
	s_mov_b32 m0, s53
	s_nop 0
	global_load_lds_dwordx4 v[20:21], off
	v_lshl_add_u64 v[20:21], s[74:75], 0, v[0:1]
	s_add_i32 m0, s53, 0x2000
	s_nop 0
	global_load_lds_dwordx4 v[20:21], off
	s_waitcnt vmcnt(4)
	s_barrier
	s_setprio 1
	v_mfma_f32_16x16x32_bf16 v[20:23], v[92:95], v[56:59], 0
	v_mfma_f32_16x16x32_bf16 v[24:27], v[100:103], v[56:59], 0
	v_mfma_f32_16x16x32_bf16 v[20:23], v[96:99], v[112:115], v[20:23]
	v_mfma_f32_16x16x32_bf16 v[24:27], v[104:107], v[112:115], v[24:27]
	v_mfma_f32_16x16x32_bf16 v[56:59], v[92:95], v[116:119], 0
	v_mfma_f32_16x16x32_bf16 v[112:115], v[100:103], v[116:119], 0
	v_mfma_f32_16x16x32_bf16 v[116:119], v[92:95], v[124:127], 0
	v_mfma_f32_16x16x32_bf16 v[92:95], v[92:95], v[142:145], 0
	v_mfma_f32_16x16x32_bf16 v[56:59], v[96:99], v[120:123], v[56:59]
	v_mfma_f32_16x16x32_bf16 v[112:115], v[104:107], v[120:123], v[112:115]
	v_mfma_f32_16x16x32_bf16 v[116:119], v[96:99], v[138:141], v[116:119]
	v_mfma_f32_16x16x32_bf16 v[120:123], v[100:103], v[124:127], 0
	v_mfma_f32_16x16x32_bf16 v[92:95], v[96:99], v[146:149], v[92:95]
	v_mfma_f32_16x16x32_bf16 v[96:99], v[100:103], v[142:145], 0
	v_mfma_f32_16x16x32_bf16 v[120:123], v[104:107], v[138:141], v[120:123]
	v_mfma_f32_16x16x32_bf16 v[96:99], v[104:107], v[146:149], v[96:99]
	s_setprio 0
	s_barrier
	ds_read_b128 v[100:103], v135
	ds_read_b128 v[104:107], v135 offset:1024
	ds_read_b128 v[124:127], v135 offset:2048
	ds_read_b128 v[138:141], v135 offset:3072
	s_mov_b32 m0, s41
	v_lshl_add_u64 v[130:131], s[12:13], 0, v[128:129]
	ds_read_b128 v[142:145], v10 offset:32768
	ds_read_b128 v[146:149], v10 offset:33792
	ds_read_b128 v[174:177], v10 offset:34816
	ds_read_b128 v[178:181], v10 offset:35840
	ds_read_b128 v[192:195], v10 offset:36864
	ds_read_b128 v[196:199], v10 offset:37888
	ds_read_b128 v[200:203], v10 offset:38912
	ds_read_b128 v[204:207], v10 offset:39936
	s_bitcmp1_b32 s100, 1
	s_cbranch_scc1 .Lpv2_b
	ds_write_b64 v248, v[208:209] offset:16384
	ds_write_b64 v249, v[210:211] offset:16384
	ds_write_b64 v248, v[212:213] offset:18432
	ds_write_b64 v249, v[214:215] offset:18432
	ds_write_b64 v248, v[216:217] offset:20480
	ds_write_b64 v249, v[218:219] offset:20480
	ds_write_b64 v248, v[220:221] offset:22528
	ds_write_b64 v249, v[222:223] offset:22528
.Lpv2_b:
	v_lshl_add_u64 v[130:131], s[12:13], 0, v[0:1]
	s_mov_b32 m0, s35
	s_nop 0
	s_waitcnt lgkmcnt(8)
	s_barrier
	s_waitcnt lgkmcnt(0)
	s_setprio 1
	s_waitcnt lgkmcnt(0)
	v_mfma_f32_16x16x32_bf16 v[60:63], v[100:103], v[142:145], v[60:63]
	v_mfma_f32_16x16x32_bf16 v[64:67], v[124:127], v[142:145], v[64:67]
	v_mfma_f32_16x16x32_bf16 v[68:71], v[100:103], v[174:177], v[68:71]
	v_mfma_f32_16x16x32_bf16 v[72:75], v[124:127], v[174:177], v[72:75]
	v_mfma_f32_16x16x32_bf16 v[76:79], v[100:103], v[192:195], v[76:79]
	v_mfma_f32_16x16x32_bf16 v[80:83], v[124:127], v[192:195], v[80:83]
	v_mfma_f32_16x16x32_bf16 v[84:87], v[100:103], v[200:203], v[84:87]
	v_mfma_f32_16x16x32_bf16 v[88:91], v[124:127], v[200:203], v[88:91]
	v_mfma_f32_16x16x32_bf16 v[60:63], v[104:107], v[146:149], v[60:63]
	v_mfma_f32_16x16x32_bf16 v[64:67], v[138:141], v[146:149], v[64:67]
	v_mfma_f32_16x16x32_bf16 v[68:71], v[104:107], v[178:181], v[68:71]
	v_mfma_f32_16x16x32_bf16 v[72:75], v[138:141], v[178:181], v[72:75]
	v_mfma_f32_16x16x32_bf16 v[76:79], v[104:107], v[196:199], v[76:79]
	v_mfma_f32_16x16x32_bf16 v[80:83], v[138:141], v[196:199], v[80:83]
	v_mfma_f32_16x16x32_bf16 v[84:87], v[104:107], v[204:207], v[84:87]
	v_mfma_f32_16x16x32_bf16 v[88:91], v[138:141], v[204:207], v[88:91]
	s_setprio 0
	s_barrier
	s_mov_b32 m0, s68
	v_lshl_add_u64 v[6:7], v[6:7], 0, s[20:21]
	ds_read_b128 v[208:211], v184
	ds_read_b128 v[212:215], v184 offset:1024
	ds_read_b128 v[216:219], v184 offset:2048
	ds_read_b128 v[220:223], v184 offset:3072
	global_load_lds_dwordx4 v[6:7], off
	v_lshl_add_u64 v[6:7], v[8:9], 0, s[20:21]
	s_mov_b32 m0, s57
	s_nop 0
	global_load_lds_dwordx4 v[6:7], off
	s_barrier
	s_waitcnt lgkmcnt(0)
	s_setprio 1
	s_waitcnt lgkmcnt(0)
	v_mfma_f32_16x16x32_bf16 v[6:9], v[208:211], v[142:145], v[108:111]
	v_mfma_f32_16x16x32_bf16 v[28:31], v[216:219], v[142:145], v[28:31]
	v_mfma_f32_16x16x32_bf16 v[32:35], v[208:211], v[174:177], v[32:35]
	v_mfma_f32_16x16x32_bf16 v[36:39], v[216:219], v[174:177], v[36:39]
	v_mfma_f32_16x16x32_bf16 v[40:43], v[208:211], v[192:195], v[40:43]
	v_mfma_f32_16x16x32_bf16 v[44:47], v[216:219], v[192:195], v[44:47]
	v_mfma_f32_16x16x32_bf16 v[48:51], v[208:211], v[200:203], v[48:51]
	v_mfma_f32_16x16x32_bf16 v[52:55], v[216:219], v[200:203], v[52:55]
	v_mfma_f32_16x16x32_bf16 v[6:9], v[212:215], v[146:149], v[6:9]
	v_mfma_f32_16x16x32_bf16 v[28:31], v[220:223], v[146:149], v[28:31]
	v_mfma_f32_16x16x32_bf16 v[32:35], v[212:215], v[178:181], v[32:35]
	v_mfma_f32_16x16x32_bf16 v[36:39], v[220:223], v[178:181], v[36:39]
	v_mfma_f32_16x16x32_bf16 v[40:43], v[212:215], v[196:199], v[40:43]
	v_mfma_f32_16x16x32_bf16 v[44:47], v[220:223], v[196:199], v[44:47]
	v_mfma_f32_16x16x32_bf16 v[48:51], v[212:215], v[204:207], v[48:51]
	v_mfma_f32_16x16x32_bf16 v[52:55], v[220:223], v[204:207], v[52:55]
	s_setprio 0
	s_mov_b32 m0, s56
	v_lshl_add_u64 v[4:5], v[4:5], 0, s[20:21]
	s_barrier
	ds_read_b128 v[108:111], v10 offset:49152
	ds_read_b128 v[142:145], v10 offset:50176
	ds_read_b128 v[146:149], v10 offset:51200
	ds_read_b128 v[174:177], v10 offset:52224
	ds_read_b128 v[178:181], v10 offset:53248
	ds_read_b128 v[192:195], v10 offset:54272
	ds_read_b128 v[196:199], v10 offset:55296
	ds_read_b128 v[200:203], v10 offset:56320
	s_bitcmp1_b32 s100, 1
	s_cbranch_scc0 .Lpv2_c
	ds_write_b64 v248, v[224:225]
	ds_write_b64 v249, v[226:227]
	ds_write_b64 v248, v[228:229] offset:2048
	ds_write_b64 v249, v[230:231] offset:2048
	ds_write_b64 v248, v[232:233] offset:4096
	ds_write_b64 v249, v[234:235] offset:4096
	ds_write_b64 v248, v[236:237] offset:6144
	ds_write_b64 v249, v[238:239] offset:6144
.Lpv2_c:
	v_lshl_add_u64 v[2:3], v[2:3], 0, s[20:21]
	s_mov_b32 m0, s40
	s_nop 0
	s_barrier
	s_waitcnt lgkmcnt(0)
	s_setprio 1
	s_waitcnt lgkmcnt(0)
	v_mfma_f32_16x16x32_bf16 v[2:5], v[100:103], v[108:111], v[150:153]
	v_mfma_f32_16x16x32_bf16 v[12:15], v[100:103], v[196:199], v[12:15]
	v_mfma_f32_16x16x32_bf16 v[16:19], v[124:127], v[196:199], v[16:19]
	v_mfma_f32_16x16x32_bf16 v[2:5], v[104:107], v[142:145], v[2:5]
	v_mfma_f32_16x16x32_bf16 v[150:153], v[124:127], v[108:111], v[154:157]
	v_mfma_f32_16x16x32_bf16 v[154:157], v[100:103], v[146:149], v[158:161]
	v_mfma_f32_16x16x32_bf16 v[158:161], v[124:127], v[146:149], v[162:165]
	v_mfma_f32_16x16x32_bf16 v[162:165], v[100:103], v[178:181], v[166:169]
	v_mfma_f32_16x16x32_bf16 v[166:169], v[124:127], v[178:181], v[170:173]
	v_mfma_f32_16x16x32_bf16 v[12:15], v[104:107], v[200:203], v[12:15]
	v_mfma_f32_16x16x32_bf16 v[16:19], v[138:141], v[200:203], v[16:19]
	v_mfma_f32_16x16x32_bf16 v[150:153], v[138:141], v[142:145], v[150:153]
	v_mfma_f32_16x16x32_bf16 v[154:157], v[104:107], v[174:177], v[154:157]
	v_mfma_f32_16x16x32_bf16 v[158:161], v[138:141], v[174:177], v[158:161]
	v_mfma_f32_16x16x32_bf16 v[162:165], v[104:107], v[192:195], v[162:165]
	v_mfma_f32_16x16x32_bf16 v[166:169], v[138:141], v[192:195], v[166:169]
	s_setprio 0
	s_barrier
	s_add_u32 s30, s30, 0x10180
	s_addc_u32 s31, s31, 0
	s_mov_b32 m0, s34
	v_lshl_add_u64 v[100:101], s[30:31], 0, v[128:129]
	global_load_lds_dwordx4 v[100:101], off
	v_lshl_add_u64 v[100:101], s[30:31], 0, v[0:1]
	s_mov_b32 m0, s33
	s_nop 0
	global_load_lds_dwordx4 v[100:101], off
	s_waitcnt vmcnt(4)
	s_barrier
	s_setprio 1
	v_mfma_f32_16x16x32_bf16 v[20:23], v[208:211], v[108:111], v[20:23]
	v_mfma_f32_16x16x32_bf16 v[24:27], v[216:219], v[108:111], v[24:27]
	v_mfma_f32_16x16x32_bf16 v[56:59], v[208:211], v[146:149], v[56:59]
	v_mfma_f32_16x16x32_bf16 v[100:103], v[216:219], v[146:149], v[112:115]
	v_mfma_f32_16x16x32_bf16 v[104:107], v[208:211], v[178:181], v[116:119]
	v_mfma_f32_16x16x32_bf16 v[108:111], v[216:219], v[178:181], v[120:123]
	v_mfma_f32_16x16x32_bf16 v[92:95], v[208:211], v[196:199], v[92:95]
	v_mfma_f32_16x16x32_bf16 v[96:99], v[216:219], v[196:199], v[96:99]
	v_mfma_f32_16x16x32_bf16 v[20:23], v[212:215], v[142:145], v[20:23]
	v_mfma_f32_16x16x32_bf16 v[24:27], v[220:223], v[142:145], v[24:27]
	v_mfma_f32_16x16x32_bf16 v[56:59], v[212:215], v[174:177], v[56:59]
	v_mfma_f32_16x16x32_bf16 v[100:103], v[220:223], v[174:177], v[100:103]
	v_mfma_f32_16x16x32_bf16 v[104:107], v[212:215], v[192:195], v[104:107]
	v_mfma_f32_16x16x32_bf16 v[108:111], v[220:223], v[192:195], v[108:111]
	v_mfma_f32_16x16x32_bf16 v[92:95], v[212:215], v[200:203], v[92:95]
	v_mfma_f32_16x16x32_bf16 v[96:99], v[220:223], v[200:203], v[96:99]
	s_setprio 0
	s_mov_b32 m0, s72
	v_lshl_add_u64 v[130:131], s[14:15], 0, v[128:129]
	s_barrier
	ds_read_b128 v[112:115], v11
	ds_read_b128 v[116:119], v11 offset:1024
	ds_read_b128 v[120:123], v11 offset:2048
	ds_read_b128 v[124:127], v11 offset:3072
	ds_read_b128 v[138:141], v10
	ds_read_b128 v[142:145], v10 offset:1024
	ds_read_b128 v[146:149], v10 offset:2048
	ds_read_b128 v[170:173], v10 offset:3072
	ds_read_b128 v[174:177], v10 offset:4096
	ds_read_b128 v[178:181], v10 offset:5120
	ds_read_b128 v[192:195], v10 offset:6144
	ds_read_b128 v[196:199], v10 offset:7168
	v_lshl_add_u64 v[0:1], s[14:15], 0, v[0:1]
	s_mov_b32 m0, s69
	s_nop 0
	s_barrier
	s_waitcnt lgkmcnt(0)
	s_setprio 1
	s_waitcnt lgkmcnt(0)
	v_mfma_f32_16x16x32_bf16 v[84:87], v[112:115], v[192:195], v[84:87]
	v_mfma_f32_16x16x32_bf16 v[60:63], v[112:115], v[138:141], v[60:63]
	v_mfma_f32_16x16x32_bf16 v[64:67], v[120:123], v[138:141], v[64:67]
	v_mfma_f32_16x16x32_bf16 v[68:71], v[112:115], v[146:149], v[68:71]
	v_mfma_f32_16x16x32_bf16 v[72:75], v[120:123], v[146:149], v[72:75]
	v_mfma_f32_16x16x32_bf16 v[76:79], v[112:115], v[174:177], v[76:79]
	v_mfma_f32_16x16x32_bf16 v[80:83], v[120:123], v[174:177], v[80:83]
	v_mfma_f32_16x16x32_bf16 v[200:203], v[116:119], v[196:199], v[84:87]
	v_mfma_f32_16x16x32_bf16 v[84:87], v[120:123], v[192:195], v[88:91]
	v_mfma_f32_16x16x32_bf16 v[60:63], v[116:119], v[142:145], v[60:63]
	v_mfma_f32_16x16x32_bf16 v[64:67], v[124:127], v[142:145], v[64:67]
	v_mfma_f32_16x16x32_bf16 v[68:71], v[116:119], v[170:173], v[68:71]
	v_mfma_f32_16x16x32_bf16 v[72:75], v[124:127], v[170:173], v[72:75]
	v_mfma_f32_16x16x32_bf16 v[76:79], v[116:119], v[178:181], v[76:79]
	v_mfma_f32_16x16x32_bf16 v[80:83], v[124:127], v[178:181], v[80:83]
	v_mfma_f32_16x16x32_bf16 v[88:91], v[124:127], v[196:199], v[84:87]
	s_setprio 0
	s_barrier
	s_nop 0
	ds_read_b128 v[84:87], v134
	ds_read_b128 v[204:207], v134 offset:1024
	ds_read_b128 v[208:211], v134 offset:2048
	ds_read_b128 v[212:215], v134 offset:3072
	s_barrier
	s_waitcnt lgkmcnt(0)
	s_setprio 1
	s_waitcnt lgkmcnt(0)
	v_mfma_f32_16x16x32_bf16 v[6:9], v[84:87], v[138:141], v[6:9]
	v_mfma_f32_16x16x32_bf16 v[28:31], v[208:211], v[138:141], v[28:31]
	v_mfma_f32_16x16x32_bf16 v[32:35], v[84:87], v[146:149], v[32:35]
	v_mfma_f32_16x16x32_bf16 v[36:39], v[208:211], v[146:149], v[36:39]
	v_mfma_f32_16x16x32_bf16 v[40:43], v[84:87], v[174:177], v[40:43]
	v_mfma_f32_16x16x32_bf16 v[44:47], v[208:211], v[174:177], v[44:47]
	v_mfma_f32_16x16x32_bf16 v[48:51], v[84:87], v[192:195], v[48:51]
	v_mfma_f32_16x16x32_bf16 v[6:9], v[204:207], v[142:145], v[6:9]
	v_mfma_f32_16x16x32_bf16 v[28:31], v[212:215], v[142:145], v[28:31]
	v_mfma_f32_16x16x32_bf16 v[32:35], v[204:207], v[170:173], v[32:35]
	v_mfma_f32_16x16x32_bf16 v[36:39], v[212:215], v[170:173], v[36:39]
	v_mfma_f32_16x16x32_bf16 v[40:43], v[204:207], v[178:181], v[40:43]
	v_mfma_f32_16x16x32_bf16 v[44:47], v[212:215], v[178:181], v[44:47]
	v_mfma_f32_16x16x32_bf16 v[48:51], v[204:207], v[196:199], v[48:51]
	v_mfma_f32_16x16x32_bf16 v[52:55], v[208:211], v[192:195], v[52:55]
	v_mfma_f32_16x16x32_bf16 v[138:141], v[212:215], v[196:199], v[52:55]
	s_setprio 0
	s_barrier
	s_nop 4
	ds_read_b128 v[52:55], v10 offset:16384
	ds_read_b128 v[142:145], v10 offset:17408
	ds_read_b128 v[146:149], v10 offset:18432
	ds_read_b128 v[170:173], v10 offset:19456
	ds_read_b128 v[174:177], v10 offset:20480
	ds_read_b128 v[178:181], v10 offset:21504
	ds_read_b128 v[192:195], v10 offset:22528
	ds_read_b128 v[196:199], v10 offset:23552
	s_waitcnt vmcnt(2)
	s_barrier
	s_waitcnt lgkmcnt(0)
	s_setprio 1
	s_waitcnt lgkmcnt(0)
	v_mfma_f32_16x16x32_bf16 v[0:3], v[112:115], v[52:55], v[2:5]
	v_mfma_f32_16x16x32_bf16 v[12:15], v[112:115], v[192:195], v[12:15]
	v_mfma_f32_16x16x32_bf16 v[0:3], v[116:119], v[142:145], v[0:3]
	v_mfma_f32_16x16x32_bf16 v[150:153], v[120:123], v[52:55], v[150:153]
	v_mfma_f32_16x16x32_bf16 v[154:157], v[112:115], v[146:149], v[154:157]
	v_mfma_f32_16x16x32_bf16 v[158:161], v[120:123], v[146:149], v[158:161]
	v_mfma_f32_16x16x32_bf16 v[162:165], v[112:115], v[174:177], v[162:165]
	v_mfma_f32_16x16x32_bf16 v[166:169], v[120:123], v[174:177], v[166:169]
	v_mfma_f32_16x16x32_bf16 v[12:15], v[116:119], v[196:199], v[12:15]
	v_mfma_f32_16x16x32_bf16 v[16:19], v[120:123], v[192:195], v[16:19]
	v_mfma_f32_16x16x32_bf16 v[150:153], v[124:127], v[142:145], v[150:153]
	v_mfma_f32_16x16x32_bf16 v[154:157], v[116:119], v[170:173], v[154:157]
	v_mfma_f32_16x16x32_bf16 v[158:161], v[124:127], v[170:173], v[158:161]
	v_mfma_f32_16x16x32_bf16 v[162:165], v[116:119], v[178:181], v[162:165]
	v_mfma_f32_16x16x32_bf16 v[166:169], v[124:127], v[178:181], v[166:169]
	v_mfma_f32_16x16x32_bf16 v[216:219], v[124:127], v[196:199], v[16:19]
	s_setprio 0
	s_setprio 1
	v_mfma_f32_16x16x32_bf16 v[16:19], v[84:87], v[52:55], v[20:23]
	v_mfma_f32_16x16x32_bf16 v[20:23], v[204:207], v[142:145], v[16:19]
	v_mfma_f32_16x16x32_bf16 v[16:19], v[208:211], v[52:55], v[24:27]
	v_mfma_f32_16x16x32_bf16 v[142:145], v[212:215], v[142:145], v[16:19]
	v_mfma_f32_16x16x32_bf16 v[16:19], v[84:87], v[146:149], v[56:59]
	v_mfma_f32_16x16x32_bf16 v[220:223], v[204:207], v[170:173], v[16:19]
	v_mfma_f32_16x16x32_bf16 v[16:19], v[208:211], v[146:149], v[100:103]
	v_mfma_f32_16x16x32_bf16 v[146:149], v[212:215], v[170:173], v[16:19]
	v_mfma_f32_16x16x32_bf16 v[16:19], v[84:87], v[174:177], v[104:107]
	v_mfma_f32_16x16x32_bf16 v[170:173], v[204:207], v[178:181], v[16:19]
	v_mfma_f32_16x16x32_bf16 v[16:19], v[208:211], v[174:177], v[108:111]
	v_mfma_f32_16x16x32_bf16 v[174:177], v[212:215], v[178:181], v[16:19]
	v_mfma_f32_16x16x32_bf16 v[16:19], v[84:87], v[192:195], v[92:95]
	v_mfma_f32_16x16x32_bf16 v[178:181], v[204:207], v[196:199], v[16:19]
	v_mfma_f32_16x16x32_bf16 v[16:19], v[208:211], v[192:195], v[96:99]
	v_mfma_f32_16x16x32_bf16 v[192:195], v[212:215], v[196:199], v[16:19]
	s_setprio 0
	s_barrier
	ds_read_b128 v[56:59], v135
	ds_read_b128 v[196:199], v135 offset:1024
	ds_read_b128 v[204:207], v135 offset:2048
	ds_read_b128 v[208:211], v135 offset:3072
	s_nop 0
	ds_read_b128 v[16:19], v10 offset:32768
	ds_read_b128 v[24:27], v10 offset:33792
	ds_read_b128 v[92:95], v10 offset:34816
	ds_read_b128 v[104:107], v10 offset:35840
	ds_read_b128 v[212:215], v10 offset:36864
	ds_read_b128 v[224:227], v10 offset:37888
	ds_read_b128 v[228:231], v10 offset:38912
	ds_read_b128 v[232:235], v10 offset:39936
	s_waitcnt vmcnt(0)
	s_barrier
	s_waitcnt lgkmcnt(0)
	s_setprio 1
	s_waitcnt lgkmcnt(0)
	v_mfma_f32_16x16x32_bf16 v[52:55], v[56:59], v[16:19], v[60:63]
	v_mfma_f32_16x16x32_bf16 v[116:119], v[196:199], v[24:27], v[52:55]
	v_mfma_f32_16x16x32_bf16 v[52:55], v[204:207], v[16:19], v[64:67]
	v_mfma_f32_16x16x32_bf16 v[112:115], v[208:211], v[24:27], v[52:55]
	v_mfma_f32_16x16x32_bf16 v[52:55], v[56:59], v[92:95], v[68:71]
	v_mfma_f32_16x16x32_bf16 v[100:103], v[196:199], v[104:107], v[52:55]
	v_mfma_f32_16x16x32_bf16 v[52:55], v[204:207], v[92:95], v[72:75]
	v_mfma_f32_16x16x32_bf16 v[96:99], v[208:211], v[104:107], v[52:55]
	v_mfma_f32_16x16x32_bf16 v[52:55], v[56:59], v[212:215], v[76:79]
	v_mfma_f32_16x16x32_bf16 v[84:87], v[196:199], v[224:227], v[52:55]
	v_mfma_f32_16x16x32_bf16 v[52:55], v[204:207], v[212:215], v[80:83]
	v_mfma_f32_16x16x32_bf16 v[80:83], v[208:211], v[224:227], v[52:55]
	v_mfma_f32_16x16x32_bf16 v[52:55], v[56:59], v[228:231], v[200:203]
	v_mfma_f32_16x16x32_bf16 v[64:67], v[196:199], v[232:235], v[52:55]
	v_mfma_f32_16x16x32_bf16 v[52:55], v[204:207], v[228:231], v[88:91]
	v_mfma_f32_16x16x32_bf16 v[52:55], v[208:211], v[232:235], v[52:55]
	s_setprio 0
	s_barrier
	ds_read_b128 v[200:203], v184
	ds_read_b128 v[236:239], v184 offset:1024
	ds_read_b128 v[240:243], v184 offset:2048
	ds_read_b128 v[244:247], v184 offset:3072
	s_waitcnt vmcnt(0)
	s_barrier
	s_waitcnt lgkmcnt(0)
	s_setprio 1
	s_waitcnt lgkmcnt(0)
	v_mfma_f32_16x16x32_bf16 v[4:7], v[200:203], v[16:19], v[6:9]
	v_mfma_f32_16x16x32_bf16 v[124:127], v[236:239], v[24:27], v[4:7]
	v_mfma_f32_16x16x32_bf16 v[4:7], v[240:243], v[16:19], v[28:31]
	v_mfma_f32_16x16x32_bf16 v[120:123], v[244:247], v[24:27], v[4:7]
	v_mfma_f32_16x16x32_bf16 v[4:7], v[200:203], v[92:95], v[32:35]
	v_mfma_f32_16x16x32_bf16 v[108:111], v[236:239], v[104:107], v[4:7]
	v_mfma_f32_16x16x32_bf16 v[4:7], v[240:243], v[92:95], v[36:39]
	v_mfma_f32_16x16x32_bf16 v[104:107], v[244:247], v[104:107], v[4:7]
	v_mfma_f32_16x16x32_bf16 v[4:7], v[200:203], v[212:215], v[40:43]
	v_mfma_f32_16x16x32_bf16 v[92:95], v[236:239], v[224:227], v[4:7]
	v_mfma_f32_16x16x32_bf16 v[4:7], v[240:243], v[212:215], v[44:47]
	v_mfma_f32_16x16x32_bf16 v[88:91], v[244:247], v[224:227], v[4:7]
	v_mfma_f32_16x16x32_bf16 v[4:7], v[200:203], v[228:231], v[48:51]
	v_mfma_f32_16x16x32_bf16 v[76:79], v[236:239], v[232:235], v[4:7]
	v_mfma_f32_16x16x32_bf16 v[4:7], v[240:243], v[228:231], v[138:141]
	v_mfma_f32_16x16x32_bf16 v[68:71], v[244:247], v[232:235], v[4:7]
	s_setprio 0
	s_barrier
	s_nop 4
	v_add_u32_e32 v10, 0x16000, v10
	ds_read_b128 v[4:7], v10 offset:49152
	ds_read_b128 v[28:31], v10 offset:50176
	ds_read_b128 v[36:39], v10 offset:51200
	ds_read_b128 v[138:141], v10 offset:52224
	ds_read_b128 v[212:215], v10 offset:53248
	ds_read_b128 v[224:227], v10 offset:54272
	ds_read_b128 v[228:231], v10 offset:55296
	ds_read_b128 v[232:235], v10 offset:56320
	s_barrier
	s_waitcnt lgkmcnt(0)
	s_setprio 1
	s_waitcnt lgkmcnt(0)
	v_mfma_f32_16x16x32_bf16 v[0:3], v[56:59], v[4:7], v[0:3]
	v_mfma_f32_16x16x32_bf16 v[60:63], v[196:199], v[28:31], v[0:3]
	v_mfma_f32_16x16x32_bf16 v[0:3], v[204:207], v[4:7], v[150:153]
	v_mfma_f32_16x16x32_bf16 v[48:51], v[208:211], v[28:31], v[0:3]
	v_mfma_f32_16x16x32_bf16 v[0:3], v[56:59], v[36:39], v[154:157]
	v_mfma_f32_16x16x32_bf16 v[40:43], v[196:199], v[138:141], v[0:3]
	v_mfma_f32_16x16x32_bf16 v[0:3], v[204:207], v[36:39], v[158:161]
	v_mfma_f32_16x16x32_bf16 v[32:35], v[208:211], v[138:141], v[0:3]
	v_mfma_f32_16x16x32_bf16 v[0:3], v[56:59], v[212:215], v[162:165]
	v_mfma_f32_16x16x32_bf16 v[24:27], v[196:199], v[224:227], v[0:3]
	v_mfma_f32_16x16x32_bf16 v[0:3], v[204:207], v[212:215], v[166:169]
	v_mfma_f32_16x16x32_bf16 v[16:19], v[208:211], v[224:227], v[0:3]
	v_mfma_f32_16x16x32_bf16 v[0:3], v[56:59], v[228:231], v[12:15]
	v_mfma_f32_16x16x32_bf16 v[8:11], v[196:199], v[232:235], v[0:3]
	v_mfma_f32_16x16x32_bf16 v[0:3], v[204:207], v[228:231], v[216:219]
	v_mfma_f32_16x16x32_bf16 v[0:3], v[208:211], v[232:235], v[0:3]
	s_setprio 0
	s_setprio 1
	v_mfma_f32_16x16x32_bf16 v[12:15], v[200:203], v[4:7], v[20:23]
	v_mfma_f32_16x16x32_bf16 v[4:7], v[240:243], v[4:7], v[142:145]
	v_mfma_f32_16x16x32_bf16 v[56:59], v[244:247], v[28:31], v[4:7]
	v_mfma_f32_16x16x32_bf16 v[4:7], v[200:203], v[36:39], v[220:223]
	v_mfma_f32_16x16x32_bf16 v[44:47], v[236:239], v[138:141], v[4:7]
	v_mfma_f32_16x16x32_bf16 v[4:7], v[240:243], v[36:39], v[146:149]
	v_mfma_f32_16x16x32_bf16 v[36:39], v[244:247], v[138:141], v[4:7]
	v_mfma_f32_16x16x32_bf16 v[4:7], v[200:203], v[212:215], v[170:173]
	v_mfma_f32_16x16x32_bf16 v[72:75], v[236:239], v[28:31], v[12:15]
	v_mfma_f32_16x16x32_bf16 v[28:31], v[236:239], v[224:227], v[4:7]
	v_mfma_f32_16x16x32_bf16 v[4:7], v[240:243], v[212:215], v[174:177]
	v_mfma_f32_16x16x32_bf16 v[20:23], v[244:247], v[224:227], v[4:7]
	v_mfma_f32_16x16x32_bf16 v[4:7], v[200:203], v[228:231], v[178:181]
	v_mfma_f32_16x16x32_bf16 v[12:15], v[236:239], v[232:235], v[4:7]
	v_mfma_f32_16x16x32_bf16 v[4:7], v[240:243], v[228:231], v[192:195]
	v_mfma_f32_16x16x32_bf16 v[4:7], v[244:247], v[232:235], v[4:7]
	s_setprio 0
	s_cmpk_gt_u32 s29, 0xff
	s_barrier
	s_cbranch_scc1 .LBB0_1066
	s_barrier
	s_branch .LBB0_1066

	.amdhsa_kernel _Z6k_mega6Params
		.amdhsa_group_segment_fixed_size 24576
		.amdhsa_private_segment_fixed_size 0
		.amdhsa_kernarg_size 896
		.amdhsa_user_sgpr_count 2
		.amdhsa_user_sgpr_dispatch_ptr 0
		.amdhsa_user_sgpr_queue_ptr 0
		.amdhsa_user_sgpr_kernarg_segment_ptr 1
		.amdhsa_user_sgpr_dispatch_id 0
		.amdhsa_user_sgpr_kernarg_preload_length 0
		.amdhsa_user_sgpr_kernarg_preload_offset 0
		.amdhsa_user_sgpr_private_segment_size 0
		.amdhsa_uses_dynamic_stack 0
		.amdhsa_enable_private_segment 0
		.amdhsa_system_sgpr_workgroup_id_x 1
		.amdhsa_system_sgpr_workgroup_id_y 0
		.amdhsa_system_sgpr_workgroup_id_z 0
		.amdhsa_system_sgpr_workgroup_info 0
		.amdhsa_system_vgpr_workitem_id 2
		.amdhsa_next_free_vgpr 256
		.amdhsa_next_free_sgpr 102
		.amdhsa_accum_offset 256
		.amdhsa_reserve_vcc 1
		.amdhsa_float_round_mode_32 0
		.amdhsa_float_round_mode_16_64 0
		.amdhsa_float_denorm_mode_32 3
		.amdhsa_float_denorm_mode_16_64 3
		.amdhsa_dx10_clamp 1
		.amdhsa_ieee_mode 1
		.amdhsa_fp16_overflow 0
		.amdhsa_tg_split 0
		.amdhsa_exception_fp_ieee_invalid_op 0
		.amdhsa_exception_fp_denorm_src 0
		.amdhsa_exception_fp_ieee_div_zero 0
		.amdhsa_exception_fp_ieee_overflow 0
		.amdhsa_exception_fp_ieee_underflow 0
		.amdhsa_exception_fp_ieee_inexact 0
		.amdhsa_exception_int_div_zero 0
	.end_amdhsa_kernel

amdhsa.kernels:
  - .agpr_count:     0
    .args:
      - .offset:         0
        .size:           640
        .value_kind:     by_value
      - .offset:         640
        .size:           4
        .value_kind:     hidden_block_count_x
      - .offset:         644
        .size:           4
        .value_kind:     hidden_block_count_y
      - .offset:         648
        .size:           4
        .value_kind:     hidden_block_count_z
      - .offset:         652
        .size:           2
        .value_kind:     hidden_group_size_x
      - .offset:         654
        .size:           2
        .value_kind:     hidden_group_size_y
      - .offset:         656
        .size:           2
        .value_kind:     hidden_group_size_z
      - .offset:         658
        .size:           2
        .value_kind:     hidden_remainder_x
      - .offset:         660
        .size:           2
        .value_kind:     hidden_remainder_y
      - .offset:         662
        .size:           2
        .value_kind:     hidden_remainder_z
      - .offset:         680
        .size:           8
        .value_kind:     hidden_global_offset_x
      - .offset:         688
        .size:           8
        .value_kind:     hidden_global_offset_y
      - .offset:         696
        .size:           8
        .value_kind:     hidden_global_offset_z
      - .offset:         704
        .size:           2
        .value_kind:     hidden_grid_dims
      - .offset:         728
        .size:           8
        .value_kind:     hidden_multigrid_sync_arg
      - .offset:         760
        .size:           4
        .value_kind:     hidden_dynamic_lds_size
    .group_segment_fixed_size: 24576
    .kernarg_segment_align: 8
    .kernarg_segment_size: 896
    .language:       OpenCL C
    .language_version:
      - 2
      - 0
    .max_flat_workgroup_size: 512
    .name:           _Z6k_mega6Params
    .private_segment_fixed_size: 0
    .sgpr_count:     108
    .sgpr_spill_count: 151
    .symbol:         _Z6k_mega6Params.kd
    .uniform_work_group_size: 1
    .uses_dynamic_stack: false
    .vgpr_count:     256
    .vgpr_spill_count: 0
    .wavefront_size: 64
